# v36 + merged K-loop waits + no s_sleep in spin loops (every bit-identical reduction stacked)
# speedup vs baseline: 1.0041x; 1.0041x over previous
; #define PG8_STAGE(bufoff, gbase, voff) do { _Pragma("unroll") for (int _i = 0; _i < 2; ++_i) \
;         __builtin_amdgcn_global_load_lds((const unsigned*)((const char*)(gbase) + (voff)[_i]), (PG8_LAS unsigned*)(lds + (bufoff) + ldsw + _i * 8192), 16, 0, 0); } while (0)
; #define PG8_LDA(dst, b, h) do { _Pragma("unroll") for (int m = 0; m < 4; ++m) _Pragma("unroll") for (int k = 0; k < 2; ++k) dst[m][k] = *(const PG8_LAS bf16x8*)(lds + PG8_SA(b, h) + aoff + m * 2048 + k * 1024); } while (0)
; #define PG8_LDB(dst, b, h) do { _Pragma("unroll") for (int n = 0; n < 2; ++n) _Pragma("unroll") for (int k = 0; k < 2; ++k) dst[n][k] = *(const PG8_LAS bf16x8*)(lds + PG8_SB(b, h) + boff + n * 2048 + k * 1024); } while (0)
; #define PG8_WAIT_V(n) asm volatile("s_waitcnt vmcnt(" #n ")" ::: "memory")
; #define PG8_WAIT_L(n) asm volatile("s_waitcnt lgkmcnt(" #n ")" ::: "memory")
; #define PG8_BAR __builtin_amdgcn_s_barrier()
; #define PG8_SCHED __builtin_amdgcn_sched_barrier(0)
; template <class Epi, class Sched, bool ALIGN_EPI = false, bool SP2 = false>
; __device__ __forceinline__ void gemm_phase(PG8_LAS unsigned char* lds, const Gemm g, const Sched& S, const Epi& E) {
;     ...
;         const bool has_next = S.next(ui + 1, nxt);
;         const char* nA = has_next ? (const char*)g.A + (size_t)nxt.pm * tstep : cA; const char* nB = has_next ? (const char*)g.Bt + (size_t)nxt.pn * tstep : cB;
;         for (int t = 0; t < nt; t += 2) {
;             if constexpr (Epi::HAS_MID) { if (t == nt / 2) E.mid(acc, cur, wr, wc, fr, fq); }
;             const bool last = (t == nt - 2);
;             const char* a1 = cA + (size_t)(t + 1) * kstep;
;             const char* a2 = last ? nA : cA + (size_t)(t + 2) * kstep; const char* b2 = last ? nB : cB + (size_t)(t + 2) * kstep;
;             const char* a3 = a2 + kstep; const char* b3 = b2 + kstep;
;             if (last && has_next) S.a_ready(nxt);
;             if constexpr (SP2) {
;             PG8_LDB(B0, 0, 0); PG8_LDB(B1, 0, 1); PG8_SCHED; PG8_LDA(At, 0, 0); PG8_STAGE(PG8_SA(1, 1), a1 + hstep, voffA);
;             PG8_WAIT_V(8); PG8_WAIT_L(0); PG8_BAR; PG8_MMA(0, 0, At, B0); PG8_MMA(0, 1, At, B1); PG8_BAR; PG8_SCHED;
;             PG8_LDA(At, 0, 1); PG8_STAGE(PG8_SB(0, 0), b2, voffB); PG8_STAGE(PG8_SB(0, 1), b2 + hstepB, voffB); PG8_STAGE(PG8_SA(0, 0), a2, voffA);
.LBB0_191:
	s_ashr_i32 s13, s12, 31
	s_lshl_b64 s[14:15], s[12:13], 19
	v_readlane_b32 s16, v241, 53
	v_readlane_b32 s17, v241, 54
	s_add_u32 s14, s16, s14
	s_addc_u32 s15, s17, s15
	s_and_b64 s[16:17], s[2:3], exec
	s_cselect_b32 s5, s15, s21
	s_cselect_b32 s13, s14, s20
	s_ashr_i32 s11, s10, 31
	s_lshl_b64 s[16:17], s[10:11], 19
	v_readlane_b32 s24, v241, 36
	v_readlane_b32 s25, v241, 37
	s_add_u32 s16, s24, s16
	s_addc_u32 s17, s25, s17
	s_and_b64 s[24:25], s[2:3], exec
	s_cselect_b32 s11, s17, s23
	s_cselect_b32 s19, s16, s22
	s_add_u32 s20, s20, 0x40080
	s_addc_u32 s21, s21, 0
	s_add_u32 s73, s22, 0x100
	s_addc_u32 s74, s23, 0
	s_mov_b32 s75, -2
	ds_read_b128 v[146:149], v152
	ds_read_b128 v[156:159], v152 offset:1024
	ds_read_b128 v[160:163], v152 offset:2048
	ds_read_b128 v[164:167], v152 offset:3072
	ds_read_b128 v[168:171], v153
	ds_read_b128 v[172:175], v153 offset:1024
	ds_read_b128 v[176:179], v153 offset:2048
	ds_read_b128 v[180:183], v153 offset:3072
	s_add_u32 s22, s20, 0xfffc0080
	s_addc_u32 s23, s21, -1
	s_cmp_eq_u32 s75, 12
	s_cselect_b32 s25, s5, s23
	s_cselect_b32 s24, s13, s22
	s_cselect_b32 s23, s11, s74
	s_cselect_b32 s22, s19, s73
	s_add_i32 m0, s27, 0xc000
	ds_read_b128 v[184:187], v154
	ds_read_b128 v[188:191], v154 offset:1024
	ds_read_b128 v[192:195], v154 offset:2048
	ds_read_b128 v[196:199], v154 offset:3072
	ds_read_b128 v[200:203], v154 offset:4096
	ds_read_b128 v[204:207], v154 offset:5120
	ds_read_b128 v[208:211], v154 offset:6144
	ds_read_b128 v[212:215], v154 offset:7168
	global_load_lds_dwordx4 v138, s[20:21]
	s_add_i32 m0, s27, 0xe000
	s_nop 0
	global_load_lds_dwordx4 v140, s[20:21]
	s_waitcnt vmcnt(8) lgkmcnt(0)
	s_barrier
	v_mfma_f32_16x16x32_bf16 v[126:129], v[146:149], v[184:187], 0
	v_mfma_f32_16x16x32_bf16 v[122:125], v[160:163], v[184:187], 0
	v_mfma_f32_16x16x32_bf16 v[114:117], v[146:149], v[192:195], 0
	v_mfma_f32_16x16x32_bf16 v[106:109], v[160:163], v[192:195], 0
	v_mfma_f32_16x16x32_bf16 v[98:101], v[146:149], v[200:203], 0
	v_mfma_f32_16x16x32_bf16 v[90:93], v[160:163], v[200:203], 0
	v_mfma_f32_16x16x32_bf16 v[82:85], v[146:149], v[208:211], 0
	v_mfma_f32_16x16x32_bf16 v[74:77], v[160:163], v[208:211], 0
	v_mfma_f32_16x16x32_bf16 v[126:129], v[156:159], v[188:191], v[126:129]
	v_mfma_f32_16x16x32_bf16 v[122:125], v[164:167], v[188:191], v[122:125]
	v_mfma_f32_16x16x32_bf16 v[114:117], v[156:159], v[196:199], v[114:117]
	v_mfma_f32_16x16x32_bf16 v[106:109], v[164:167], v[196:199], v[106:109]
	v_mfma_f32_16x16x32_bf16 v[98:101], v[156:159], v[204:207], v[98:101]
	v_mfma_f32_16x16x32_bf16 v[90:93], v[164:167], v[204:207], v[90:93]
	v_mfma_f32_16x16x32_bf16 v[82:85], v[156:159], v[212:215], v[82:85]
	v_mfma_f32_16x16x32_bf16 v[74:77], v[164:167], v[212:215], v[74:77]
	v_mfma_f32_16x16x32_bf16 v[118:121], v[168:171], v[184:187], 0
	v_mfma_f32_16x16x32_bf16 v[110:113], v[176:179], v[184:187], 0
	v_mfma_f32_16x16x32_bf16 v[102:105], v[168:171], v[192:195], 0
	v_mfma_f32_16x16x32_bf16 v[94:97], v[176:179], v[192:195], 0
	v_mfma_f32_16x16x32_bf16 v[86:89], v[168:171], v[200:203], 0
	v_mfma_f32_16x16x32_bf16 v[78:81], v[176:179], v[200:203], 0
	v_mfma_f32_16x16x32_bf16 v[70:73], v[168:171], v[208:211], 0
	v_mfma_f32_16x16x32_bf16 v[66:69], v[176:179], v[208:211], 0
	v_mfma_f32_16x16x32_bf16 v[118:121], v[172:175], v[188:191], v[118:121]
	v_mfma_f32_16x16x32_bf16 v[110:113], v[180:183], v[188:191], v[110:113]
	v_mfma_f32_16x16x32_bf16 v[102:105], v[172:175], v[196:199], v[102:105]
	v_mfma_f32_16x16x32_bf16 v[94:97], v[180:183], v[196:199], v[94:97]
	v_mfma_f32_16x16x32_bf16 v[86:89], v[172:175], v[204:207], v[86:89]
	v_mfma_f32_16x16x32_bf16 v[78:81], v[180:183], v[204:207], v[78:81]
	v_mfma_f32_16x16x32_bf16 v[70:73], v[172:175], v[212:215], v[70:73]
	v_mfma_f32_16x16x32_bf16 v[66:69], v[180:183], v[212:215], v[66:69]
	s_barrier
	s_add_i32 s76, s69, s26
	v_lshl_add_u64 v[216:217], s[22:23], 0, v[132:133]
	s_mov_b32 m0, s76
	ds_read_b128 v[184:187], v154 offset:16384
	ds_read_b128 v[188:191], v154 offset:17408
	ds_read_b128 v[192:195], v154 offset:18432
	ds_read_b128 v[196:199], v154 offset:19456
	ds_read_b128 v[200:203], v154 offset:20480
	ds_read_b128 v[204:207], v154 offset:21504
	ds_read_b128 v[208:211], v154 offset:22528
	ds_read_b128 v[212:215], v154 offset:23552
	global_load_lds_dwordx4 v132, s[22:23]
	s_add_i32 m0, s76, 0x2000
	s_add_u32 s76, s22, 0x10000
	v_lshl_add_u64 v[218:219], s[22:23], 0, v[136:137]
	s_addc_u32 s77, s23, 0
	s_add_i32 s78, s70, s26
	global_load_lds_dwordx4 v136, s[22:23]
	s_mov_b32 m0, s78
	v_lshl_add_u64 v[222:223], s[24:25], 0, v[134:135]
	global_load_lds_dwordx4 v132, s[76:77]
	s_add_i32 m0, s78, 0x2000
	s_nop 0
	global_load_lds_dwordx4 v136, s[76:77]
	v_lshl_add_u64 v[220:221], s[24:25], 0, v[130:131]
	s_mov_b32 m0, s27
	s_nop 0
	global_load_lds_dwordx4 v130, s[24:25]
	s_mov_b32 m0, s28
	s_nop 0
	global_load_lds_dwordx4 v134, s[24:25]
	s_waitcnt vmcnt(8) lgkmcnt(0)
	s_barrier
; #define PG8_STAGE(bufoff, gbase, voff) do { _Pragma("unroll") for (int _i = 0; _i < 2; ++_i) \
;         __builtin_amdgcn_global_load_lds((const unsigned*)((const char*)(gbase) + (voff)[_i]), (PG8_LAS unsigned*)(lds + (bufoff) + ldsw + _i * 8192), 16, 0, 0); } while (0)
; #define PG8_LDA(dst, b, h) do { _Pragma("unroll") for (int m = 0; m < 4; ++m) _Pragma("unroll") for (int k = 0; k < 2; ++k) dst[m][k] = *(const PG8_LAS bf16x8*)(lds + PG8_SA(b, h) + aoff + m * 2048 + k * 1024); } while (0)
; #define PG8_LDB(dst, b, h) do { _Pragma("unroll") for (int n = 0; n < 2; ++n) _Pragma("unroll") for (int k = 0; k < 2; ++k) dst[n][k] = *(const PG8_LAS bf16x8*)(lds + PG8_SB(b, h) + boff + n * 2048 + k * 1024); } while (0)
; #define PG8_MMA(ai, bj, At, Bt) do { __builtin_amdgcn_s_setprio(1); _Pragma("unroll") for (int m = 0; m < 4; ++m) _Pragma("unroll") for (int n = 0; n < 2; ++n) _Pragma("unroll") for (int k = 0; k < 2; ++k) \
;         acc[ai][bj][m][n] = __builtin_amdgcn_mfma_f32_16x16x32_bf16(Bt[n][k], At[m][k], acc[ai][bj][m][n], 0, 0, 0); __builtin_amdgcn_s_setprio(0); } while (0)
; #define PG8_WAIT_V(n) asm volatile("s_waitcnt vmcnt(" #n ")" ::: "memory")
; #define PG8_WAIT_L(n) asm volatile("s_waitcnt lgkmcnt(" #n ")" ::: "memory")
; #define PG8_BAR __builtin_amdgcn_s_barrier()
; #define PG8_SCHED __builtin_amdgcn_sched_barrier(0)
; template <class Epi, class Sched, bool ALIGN_EPI = false, bool SP2 = false>
; __device__ __forceinline__ void gemm_phase(PG8_LAS unsigned char* lds, const Gemm g, const Sched& S, const Epi& E) {
;     ...
;             PG8_WAIT_V(8); PG8_WAIT_L(0); PG8_BAR; PG8_MMA(1, 0, At, B0); PG8_MMA(1, 1, At, B1); PG8_BAR; PG8_SCHED;
;             PG8_LDB(B0, 1, 0); PG8_LDB(B1, 1, 1); PG8_SCHED; PG8_LDA(At, 1, 0); PG8_STAGE(PG8_SA(0, 1), a2 + hstep, voffA);
;             PG8_WAIT_V(8); PG8_WAIT_L(0); PG8_BAR; PG8_MMA(0, 0, At, B0); PG8_MMA(0, 1, At, B1); PG8_BAR; PG8_SCHED;
	v_mfma_f32_16x16x32_bf16 v[62:65], v[146:149], v[184:187], 0
	v_mfma_f32_16x16x32_bf16 v[58:61], v[160:163], v[184:187], 0
	v_mfma_f32_16x16x32_bf16 v[50:53], v[146:149], v[192:195], 0
	v_mfma_f32_16x16x32_bf16 v[42:45], v[160:163], v[192:195], 0
	v_mfma_f32_16x16x32_bf16 v[34:37], v[146:149], v[200:203], 0
	v_mfma_f32_16x16x32_bf16 v[26:29], v[160:163], v[200:203], 0
	v_mfma_f32_16x16x32_bf16 v[18:21], v[146:149], v[208:211], 0
	v_mfma_f32_16x16x32_bf16 v[10:13], v[160:163], v[208:211], 0
	v_mfma_f32_16x16x32_bf16 v[62:65], v[156:159], v[188:191], v[62:65]
	v_mfma_f32_16x16x32_bf16 v[58:61], v[164:167], v[188:191], v[58:61]
	v_mfma_f32_16x16x32_bf16 v[50:53], v[156:159], v[196:199], v[50:53]
	v_mfma_f32_16x16x32_bf16 v[42:45], v[164:167], v[196:199], v[42:45]
	v_mfma_f32_16x16x32_bf16 v[34:37], v[156:159], v[204:207], v[34:37]
	v_mfma_f32_16x16x32_bf16 v[26:29], v[164:167], v[204:207], v[26:29]
	v_mfma_f32_16x16x32_bf16 v[18:21], v[156:159], v[212:215], v[18:21]
	v_mfma_f32_16x16x32_bf16 v[10:13], v[164:167], v[212:215], v[10:13]
	v_mfma_f32_16x16x32_bf16 v[54:57], v[168:171], v[184:187], 0
	v_mfma_f32_16x16x32_bf16 v[46:49], v[176:179], v[184:187], 0
	v_mfma_f32_16x16x32_bf16 v[38:41], v[168:171], v[192:195], 0
	v_mfma_f32_16x16x32_bf16 v[30:33], v[176:179], v[192:195], 0
	v_mfma_f32_16x16x32_bf16 v[22:25], v[168:171], v[200:203], 0
	v_mfma_f32_16x16x32_bf16 v[14:17], v[176:179], v[200:203], 0
	v_mfma_f32_16x16x32_bf16 v[6:9], v[168:171], v[208:211], 0
	v_mfma_f32_16x16x32_bf16 v[2:5], v[176:179], v[208:211], 0
	v_mfma_f32_16x16x32_bf16 v[54:57], v[172:175], v[188:191], v[54:57]
	v_mfma_f32_16x16x32_bf16 v[46:49], v[180:183], v[188:191], v[46:49]
	v_mfma_f32_16x16x32_bf16 v[38:41], v[172:175], v[196:199], v[38:41]
	v_mfma_f32_16x16x32_bf16 v[30:33], v[180:183], v[196:199], v[30:33]
	v_mfma_f32_16x16x32_bf16 v[22:25], v[172:175], v[204:207], v[22:25]
	v_mfma_f32_16x16x32_bf16 v[14:17], v[180:183], v[204:207], v[14:17]
	v_mfma_f32_16x16x32_bf16 v[6:9], v[172:175], v[212:215], v[6:9]
	v_mfma_f32_16x16x32_bf16 v[2:5], v[180:183], v[212:215], v[2:5]
	s_barrier
	s_add_i32 s76, 0, 0x18000
	v_add_u32_e32 v155, s76, v150
	s_add_i32 s77, 0, 0x1c000
	ds_read_b128 v[146:149], v155
	ds_read_b128 v[156:159], v155 offset:1024
	ds_read_b128 v[160:163], v155 offset:2048
	ds_read_b128 v[164:167], v155 offset:3072
	v_add_u32_e32 v155, s77, v150
	ds_read_b128 v[168:171], v155
	ds_read_b128 v[172:175], v155 offset:1024
	ds_read_b128 v[176:179], v155 offset:2048
	ds_read_b128 v[180:183], v155 offset:3072
	s_add_u32 s24, s24, 0x40000
	s_addc_u32 s25, s25, 0
	s_mov_b32 m0, s29
	ds_read_b128 v[184:187], v154 offset:32768
	ds_read_b128 v[188:191], v154 offset:33792
	ds_read_b128 v[192:195], v154 offset:34816
	ds_read_b128 v[196:199], v154 offset:35840
	ds_read_b128 v[200:203], v154 offset:36864
	ds_read_b128 v[204:207], v154 offset:37888
	ds_read_b128 v[208:211], v154 offset:38912
	ds_read_b128 v[212:215], v154 offset:39936
	global_load_lds_dwordx4 v130, s[24:25]
	s_mov_b32 m0, s30
	s_nop 0
	global_load_lds_dwordx4 v134, s[24:25]
	s_waitcnt vmcnt(8) lgkmcnt(0)
	s_barrier
	v_mfma_f32_16x16x32_bf16 v[126:129], v[146:149], v[184:187], v[126:129]
	v_mfma_f32_16x16x32_bf16 v[122:125], v[160:163], v[184:187], v[122:125]
	v_mfma_f32_16x16x32_bf16 v[114:117], v[146:149], v[192:195], v[114:117]
	v_mfma_f32_16x16x32_bf16 v[106:109], v[160:163], v[192:195], v[106:109]
	v_mfma_f32_16x16x32_bf16 v[98:101], v[146:149], v[200:203], v[98:101]
	v_mfma_f32_16x16x32_bf16 v[90:93], v[160:163], v[200:203], v[90:93]
	v_mfma_f32_16x16x32_bf16 v[82:85], v[146:149], v[208:211], v[82:85]
	v_mfma_f32_16x16x32_bf16 v[74:77], v[160:163], v[208:211], v[74:77]
	v_mfma_f32_16x16x32_bf16 v[126:129], v[156:159], v[188:191], v[126:129]
	v_mfma_f32_16x16x32_bf16 v[122:125], v[164:167], v[188:191], v[122:125]
	v_mfma_f32_16x16x32_bf16 v[114:117], v[156:159], v[196:199], v[114:117]
	v_mfma_f32_16x16x32_bf16 v[106:109], v[164:167], v[196:199], v[106:109]
	v_mfma_f32_16x16x32_bf16 v[98:101], v[156:159], v[204:207], v[98:101]
	v_mfma_f32_16x16x32_bf16 v[90:93], v[164:167], v[204:207], v[90:93]
	v_mfma_f32_16x16x32_bf16 v[82:85], v[156:159], v[212:215], v[82:85]
	v_mfma_f32_16x16x32_bf16 v[74:77], v[164:167], v[212:215], v[74:77]
	v_mfma_f32_16x16x32_bf16 v[118:121], v[168:171], v[184:187], v[118:121]
	v_mfma_f32_16x16x32_bf16 v[110:113], v[176:179], v[184:187], v[110:113]
	v_mfma_f32_16x16x32_bf16 v[102:105], v[168:171], v[192:195], v[102:105]
	v_mfma_f32_16x16x32_bf16 v[94:97], v[176:179], v[192:195], v[94:97]
	v_mfma_f32_16x16x32_bf16 v[86:89], v[168:171], v[200:203], v[86:89]
	v_mfma_f32_16x16x32_bf16 v[78:81], v[176:179], v[200:203], v[78:81]
	v_mfma_f32_16x16x32_bf16 v[70:73], v[168:171], v[208:211], v[70:73]
	v_mfma_f32_16x16x32_bf16 v[66:69], v[176:179], v[208:211], v[66:69]
	v_mfma_f32_16x16x32_bf16 v[118:121], v[172:175], v[188:191], v[118:121]
	v_mfma_f32_16x16x32_bf16 v[110:113], v[180:183], v[188:191], v[110:113]
	v_mfma_f32_16x16x32_bf16 v[102:105], v[172:175], v[196:199], v[102:105]
	v_mfma_f32_16x16x32_bf16 v[94:97], v[180:183], v[196:199], v[94:97]
	v_mfma_f32_16x16x32_bf16 v[86:89], v[172:175], v[204:207], v[86:89]
	v_mfma_f32_16x16x32_bf16 v[78:81], v[180:183], v[204:207], v[78:81]
	v_mfma_f32_16x16x32_bf16 v[70:73], v[172:175], v[212:215], v[70:73]
	v_mfma_f32_16x16x32_bf16 v[66:69], v[180:183], v[212:215], v[66:69]
	s_barrier
; #define PG8_STAGE(bufoff, gbase, voff) do { _Pragma("unroll") for (int _i = 0; _i < 2; ++_i) \
;         __builtin_amdgcn_global_load_lds((const unsigned*)((const char*)(gbase) + (voff)[_i]), (PG8_LAS unsigned*)(lds + (bufoff) + ldsw + _i * 8192), 16, 0, 0); } while (0)
; #define PG8_LDA(dst, b, h) do { _Pragma("unroll") for (int m = 0; m < 4; ++m) _Pragma("unroll") for (int k = 0; k < 2; ++k) dst[m][k] = *(const PG8_LAS bf16x8*)(lds + PG8_SA(b, h) + aoff + m * 2048 + k * 1024); } while (0)
; #define PG8_LDB(dst, b, h) do { _Pragma("unroll") for (int n = 0; n < 2; ++n) _Pragma("unroll") for (int k = 0; k < 2; ++k) dst[n][k] = *(const PG8_LAS bf16x8*)(lds + PG8_SB(b, h) + boff + n * 2048 + k * 1024); } while (0)
; #define PG8_MMA(ai, bj, At, Bt) do { __builtin_amdgcn_s_setprio(1); _Pragma("unroll") for (int m = 0; m < 4; ++m) _Pragma("unroll") for (int n = 0; n < 2; ++n) _Pragma("unroll") for (int k = 0; k < 2; ++k) \
;         acc[ai][bj][m][n] = __builtin_amdgcn_mfma_f32_16x16x32_bf16(Bt[n][k], At[m][k], acc[ai][bj][m][n], 0, 0, 0); __builtin_amdgcn_s_setprio(0); } while (0)
; #define PG8_WAIT_V(n) asm volatile("s_waitcnt vmcnt(" #n ")" ::: "memory")
; #define PG8_WAIT_L(n) asm volatile("s_waitcnt lgkmcnt(" #n ")" ::: "memory")
; template <class Epi, class Sched, bool ALIGN_EPI = false, bool SP2 = false>
; __device__ __forceinline__ void gemm_phase(PG8_LAS unsigned char* lds, const Gemm g, const Sched& S, const Epi& E) {
;     ...
;             const bool last = (t == nt - 2);
;             const char* a1 = cA + (size_t)(t + 1) * kstep;
;             const char* a2 = last ? nA : cA + (size_t)(t + 2) * kstep; const char* b2 = last ? nB : cB + (size_t)(t + 2) * kstep;
;             const char* a3 = a2 + kstep; const char* b3 = b2 + kstep;
;             if (last && has_next) S.a_ready(nxt);
;             if constexpr (SP2) {
;             PG8_LDB(B0, 0, 0); PG8_LDB(B1, 0, 1); PG8_SCHED; PG8_LDA(At, 0, 0); PG8_STAGE(PG8_SA(1, 1), a1 + hstep, voffA);
;             PG8_WAIT_V(8); PG8_WAIT_L(0); PG8_BAR; PG8_MMA(0, 0, At, B0); PG8_MMA(0, 1, At, B1); PG8_BAR; PG8_SCHED;
;     ...
;             PG8_LDA(At, 1, 1); PG8_STAGE(PG8_SB(1, 0), b3, voffB); PG8_STAGE(PG8_SB(1, 1), b3 + hstepB, voffB); PG8_STAGE(PG8_SA(1, 0), a3, voffA);
;             PG8_WAIT_V(8); PG8_WAIT_L(0); PG8_BAR; PG8_MMA(1, 0, At, B0); PG8_MMA(1, 1, At, B1); PG8_BAR; PG8_SCHED;
	s_add_i32 s24, s76, s26
	v_lshl_add_u64 v[216:217], v[216:217], 0, s[6:7]
	s_mov_b32 m0, s24
	ds_read_b128 v[184:187], v154 offset:49152
	ds_read_b128 v[188:191], v154 offset:50176
	ds_read_b128 v[192:195], v154 offset:51200
	ds_read_b128 v[196:199], v154 offset:52224
	ds_read_b128 v[200:203], v154 offset:53248
	ds_read_b128 v[204:207], v154 offset:54272
	ds_read_b128 v[208:211], v154 offset:55296
	ds_read_b128 v[212:215], v154 offset:56320
	global_load_lds_dwordx4 v[216:217], off
	s_add_i32 m0, s24, 0x2000
	s_add_u32 s22, s22, 0x10080
	v_lshl_add_u64 v[216:217], v[218:219], 0, s[6:7]
	s_addc_u32 s23, s23, 0
	s_add_i32 s24, s77, s26
	global_load_lds_dwordx4 v[216:217], off
	s_mov_b32 m0, s24
	s_nop 0
	global_load_lds_dwordx4 v132, s[22:23]
	s_add_i32 m0, s24, 0x2000
	s_nop 0
	global_load_lds_dwordx4 v136, s[22:23]
	v_lshl_add_u64 v[216:217], v[220:221], 0, s[6:7]
	s_mov_b32 m0, s33
	s_nop 0
	global_load_lds_dwordx4 v[216:217], off
	v_lshl_add_u64 v[216:217], v[222:223], 0, s[6:7]
	s_mov_b32 m0, s34
	s_nop 0
	global_load_lds_dwordx4 v[216:217], off
	s_waitcnt vmcnt(8) lgkmcnt(0)
	s_barrier
	v_mfma_f32_16x16x32_bf16 v[62:65], v[146:149], v[184:187], v[62:65]
	v_mfma_f32_16x16x32_bf16 v[58:61], v[160:163], v[184:187], v[58:61]
	v_mfma_f32_16x16x32_bf16 v[50:53], v[146:149], v[192:195], v[50:53]
	v_mfma_f32_16x16x32_bf16 v[42:45], v[160:163], v[192:195], v[42:45]
	v_mfma_f32_16x16x32_bf16 v[34:37], v[146:149], v[200:203], v[34:37]
	v_mfma_f32_16x16x32_bf16 v[26:29], v[160:163], v[200:203], v[26:29]
	v_mfma_f32_16x16x32_bf16 v[18:21], v[146:149], v[208:211], v[18:21]
	v_mfma_f32_16x16x32_bf16 v[10:13], v[160:163], v[208:211], v[10:13]
	v_mfma_f32_16x16x32_bf16 v[62:65], v[156:159], v[188:191], v[62:65]
	v_mfma_f32_16x16x32_bf16 v[58:61], v[164:167], v[188:191], v[58:61]
	v_mfma_f32_16x16x32_bf16 v[50:53], v[156:159], v[196:199], v[50:53]
	v_mfma_f32_16x16x32_bf16 v[42:45], v[164:167], v[196:199], v[42:45]
	v_mfma_f32_16x16x32_bf16 v[34:37], v[156:159], v[204:207], v[34:37]
	v_mfma_f32_16x16x32_bf16 v[26:29], v[164:167], v[204:207], v[26:29]
	v_mfma_f32_16x16x32_bf16 v[18:21], v[156:159], v[212:215], v[18:21]
	v_mfma_f32_16x16x32_bf16 v[10:13], v[164:167], v[212:215], v[10:13]
	v_mfma_f32_16x16x32_bf16 v[54:57], v[168:171], v[184:187], v[54:57]
	v_mfma_f32_16x16x32_bf16 v[46:49], v[176:179], v[184:187], v[46:49]
	v_mfma_f32_16x16x32_bf16 v[38:41], v[168:171], v[192:195], v[38:41]
	v_mfma_f32_16x16x32_bf16 v[30:33], v[176:179], v[192:195], v[30:33]
	v_mfma_f32_16x16x32_bf16 v[22:25], v[168:171], v[200:203], v[22:25]
	v_mfma_f32_16x16x32_bf16 v[14:17], v[176:179], v[200:203], v[14:17]
	v_mfma_f32_16x16x32_bf16 v[6:9], v[168:171], v[208:211], v[6:9]
	v_mfma_f32_16x16x32_bf16 v[2:5], v[176:179], v[208:211], v[2:5]
	v_mfma_f32_16x16x32_bf16 v[54:57], v[172:175], v[188:191], v[54:57]
	v_mfma_f32_16x16x32_bf16 v[46:49], v[180:183], v[188:191], v[46:49]
	v_mfma_f32_16x16x32_bf16 v[38:41], v[172:175], v[196:199], v[38:41]
	v_mfma_f32_16x16x32_bf16 v[30:33], v[180:183], v[196:199], v[30:33]
	v_mfma_f32_16x16x32_bf16 v[22:25], v[172:175], v[204:207], v[22:25]
	v_mfma_f32_16x16x32_bf16 v[14:17], v[180:183], v[204:207], v[14:17]
	v_mfma_f32_16x16x32_bf16 v[6:9], v[172:175], v[212:215], v[6:9]
	v_mfma_f32_16x16x32_bf16 v[2:5], v[180:183], v[212:215], v[2:5]
	s_barrier
	s_add_i32 s75, s75, 2
	s_add_u32 s20, s20, 0x100
	s_addc_u32 s21, s21, 0
	s_add_u32 s73, s73, 0x100
	s_addc_u32 s74, s74, 0
	s_cmp_gt_u32 s75, 13
	s_cbranch_scc1 .Lpp0_x
.LBB0_192:
	ds_read_b128 v[146:149], v152
	ds_read_b128 v[156:159], v152 offset:1024
	ds_read_b128 v[160:163], v152 offset:2048
	ds_read_b128 v[164:167], v152 offset:3072
	ds_read_b128 v[168:171], v153
	ds_read_b128 v[172:175], v153 offset:1024
	ds_read_b128 v[176:179], v153 offset:2048
	ds_read_b128 v[180:183], v153 offset:3072
	s_add_u32 s22, s20, 0xfffc0080
	s_addc_u32 s23, s21, -1
	s_cmp_eq_u32 s75, 12
	s_cselect_b32 s25, s5, s23
	s_cselect_b32 s24, s13, s22
	s_cselect_b32 s23, s11, s74
	s_cselect_b32 s22, s19, s73
	s_add_i32 m0, s27, 0xc000
	ds_read_b128 v[184:187], v154
	ds_read_b128 v[188:191], v154 offset:1024
	ds_read_b128 v[192:195], v154 offset:2048
	ds_read_b128 v[196:199], v154 offset:3072
	ds_read_b128 v[200:203], v154 offset:4096
	ds_read_b128 v[204:207], v154 offset:5120
	ds_read_b128 v[208:211], v154 offset:6144
	ds_read_b128 v[212:215], v154 offset:7168
	global_load_lds_dwordx4 v138, s[20:21]
	s_add_i32 m0, s27, 0xe000
	s_nop 0
	global_load_lds_dwordx4 v140, s[20:21]
	s_waitcnt vmcnt(8) lgkmcnt(0)
	s_barrier
; #define PG8_STAGE(bufoff, gbase, voff) do { _Pragma("unroll") for (int _i = 0; _i < 2; ++_i) \
;         __builtin_amdgcn_global_load_lds((const unsigned*)((const char*)(gbase) + (voff)[_i]), (PG8_LAS unsigned*)(lds + (bufoff) + ldsw + _i * 8192), 16, 0, 0); } while (0)
; #define PG8_LDA(dst, b, h) do { _Pragma("unroll") for (int m = 0; m < 4; ++m) _Pragma("unroll") for (int k = 0; k < 2; ++k) dst[m][k] = *(const PG8_LAS bf16x8*)(lds + PG8_SA(b, h) + aoff + m * 2048 + k * 1024); } while (0)
; #define PG8_MMA(ai, bj, At, Bt) do { __builtin_amdgcn_s_setprio(1); _Pragma("unroll") for (int m = 0; m < 4; ++m) _Pragma("unroll") for (int n = 0; n < 2; ++n) _Pragma("unroll") for (int k = 0; k < 2; ++k) \
;         acc[ai][bj][m][n] = __builtin_amdgcn_mfma_f32_16x16x32_bf16(Bt[n][k], At[m][k], acc[ai][bj][m][n], 0, 0, 0); __builtin_amdgcn_s_setprio(0); } while (0)
; #define PG8_WAIT_V(n) asm volatile("s_waitcnt vmcnt(" #n ")" ::: "memory")
; #define PG8_WAIT_L(n) asm volatile("s_waitcnt lgkmcnt(" #n ")" ::: "memory")
; #define PG8_BAR __builtin_amdgcn_s_barrier()
; #define PG8_SCHED __builtin_amdgcn_sched_barrier(0)
; template <class Epi, class Sched, bool ALIGN_EPI = false, bool SP2 = false>
; __device__ __forceinline__ void gemm_phase(PG8_LAS unsigned char* lds, const Gemm g, const Sched& S, const Epi& E) {
;     ...
;             PG8_WAIT_V(8); PG8_WAIT_L(0); PG8_BAR; PG8_MMA(0, 0, At, B0); PG8_MMA(0, 1, At, B1); PG8_BAR; PG8_SCHED;
;             PG8_LDA(At, 0, 1); PG8_STAGE(PG8_SB(0, 0), b2, voffB); PG8_STAGE(PG8_SB(0, 1), b2 + hstepB, voffB); PG8_STAGE(PG8_SA(0, 0), a2, voffA);
;             PG8_WAIT_V(8); PG8_WAIT_L(0); PG8_BAR; PG8_MMA(1, 0, At, B0); PG8_MMA(1, 1, At, B1); PG8_BAR; PG8_SCHED;
	v_mfma_f32_16x16x32_bf16 v[126:129], v[146:149], v[184:187], v[126:129]
	v_mfma_f32_16x16x32_bf16 v[122:125], v[160:163], v[184:187], v[122:125]
	v_mfma_f32_16x16x32_bf16 v[114:117], v[146:149], v[192:195], v[114:117]
	v_mfma_f32_16x16x32_bf16 v[106:109], v[160:163], v[192:195], v[106:109]
	v_mfma_f32_16x16x32_bf16 v[98:101], v[146:149], v[200:203], v[98:101]
	v_mfma_f32_16x16x32_bf16 v[90:93], v[160:163], v[200:203], v[90:93]
	v_mfma_f32_16x16x32_bf16 v[82:85], v[146:149], v[208:211], v[82:85]
	v_mfma_f32_16x16x32_bf16 v[74:77], v[160:163], v[208:211], v[74:77]
	v_mfma_f32_16x16x32_bf16 v[126:129], v[156:159], v[188:191], v[126:129]
	v_mfma_f32_16x16x32_bf16 v[122:125], v[164:167], v[188:191], v[122:125]
	v_mfma_f32_16x16x32_bf16 v[114:117], v[156:159], v[196:199], v[114:117]
	v_mfma_f32_16x16x32_bf16 v[106:109], v[164:167], v[196:199], v[106:109]
	v_mfma_f32_16x16x32_bf16 v[98:101], v[156:159], v[204:207], v[98:101]
	v_mfma_f32_16x16x32_bf16 v[90:93], v[164:167], v[204:207], v[90:93]
	v_mfma_f32_16x16x32_bf16 v[82:85], v[156:159], v[212:215], v[82:85]
	v_mfma_f32_16x16x32_bf16 v[74:77], v[164:167], v[212:215], v[74:77]
	v_mfma_f32_16x16x32_bf16 v[118:121], v[168:171], v[184:187], v[118:121]
	v_mfma_f32_16x16x32_bf16 v[110:113], v[176:179], v[184:187], v[110:113]
	v_mfma_f32_16x16x32_bf16 v[102:105], v[168:171], v[192:195], v[102:105]
	v_mfma_f32_16x16x32_bf16 v[94:97], v[176:179], v[192:195], v[94:97]
	v_mfma_f32_16x16x32_bf16 v[86:89], v[168:171], v[200:203], v[86:89]
	v_mfma_f32_16x16x32_bf16 v[78:81], v[176:179], v[200:203], v[78:81]
	v_mfma_f32_16x16x32_bf16 v[70:73], v[168:171], v[208:211], v[70:73]
	v_mfma_f32_16x16x32_bf16 v[66:69], v[176:179], v[208:211], v[66:69]
	v_mfma_f32_16x16x32_bf16 v[118:121], v[172:175], v[188:191], v[118:121]
	v_mfma_f32_16x16x32_bf16 v[110:113], v[180:183], v[188:191], v[110:113]
	v_mfma_f32_16x16x32_bf16 v[102:105], v[172:175], v[196:199], v[102:105]
	v_mfma_f32_16x16x32_bf16 v[94:97], v[180:183], v[196:199], v[94:97]
	v_mfma_f32_16x16x32_bf16 v[86:89], v[172:175], v[204:207], v[86:89]
	v_mfma_f32_16x16x32_bf16 v[78:81], v[180:183], v[204:207], v[78:81]
	v_mfma_f32_16x16x32_bf16 v[70:73], v[172:175], v[212:215], v[70:73]
	v_mfma_f32_16x16x32_bf16 v[66:69], v[180:183], v[212:215], v[66:69]
	s_barrier
	s_add_i32 s76, s69, s26
	v_lshl_add_u64 v[216:217], s[22:23], 0, v[132:133]
	s_mov_b32 m0, s76
	ds_read_b128 v[184:187], v154 offset:16384
	ds_read_b128 v[188:191], v154 offset:17408
	ds_read_b128 v[192:195], v154 offset:18432
	ds_read_b128 v[196:199], v154 offset:19456
	ds_read_b128 v[200:203], v154 offset:20480
	ds_read_b128 v[204:207], v154 offset:21504
	ds_read_b128 v[208:211], v154 offset:22528
	ds_read_b128 v[212:215], v154 offset:23552
	global_load_lds_dwordx4 v132, s[22:23]
	s_add_i32 m0, s76, 0x2000
	s_add_u32 s76, s22, 0x10000
	v_lshl_add_u64 v[218:219], s[22:23], 0, v[136:137]
	s_addc_u32 s77, s23, 0
	s_add_i32 s78, s70, s26
	global_load_lds_dwordx4 v136, s[22:23]
	s_mov_b32 m0, s78
	v_lshl_add_u64 v[222:223], s[24:25], 0, v[134:135]
	global_load_lds_dwordx4 v132, s[76:77]
	s_add_i32 m0, s78, 0x2000
	s_nop 0
	global_load_lds_dwordx4 v136, s[76:77]
	v_lshl_add_u64 v[220:221], s[24:25], 0, v[130:131]
	s_mov_b32 m0, s27
	s_nop 0
	global_load_lds_dwordx4 v130, s[24:25]
	s_mov_b32 m0, s28
	s_nop 0
	global_load_lds_dwordx4 v134, s[24:25]
	s_waitcnt vmcnt(8) lgkmcnt(0)
	s_barrier
	v_mfma_f32_16x16x32_bf16 v[62:65], v[146:149], v[184:187], v[62:65]
	v_mfma_f32_16x16x32_bf16 v[58:61], v[160:163], v[184:187], v[58:61]
	v_mfma_f32_16x16x32_bf16 v[50:53], v[146:149], v[192:195], v[50:53]
	v_mfma_f32_16x16x32_bf16 v[42:45], v[160:163], v[192:195], v[42:45]
	v_mfma_f32_16x16x32_bf16 v[34:37], v[146:149], v[200:203], v[34:37]
	v_mfma_f32_16x16x32_bf16 v[26:29], v[160:163], v[200:203], v[26:29]
	v_mfma_f32_16x16x32_bf16 v[18:21], v[146:149], v[208:211], v[18:21]
	v_mfma_f32_16x16x32_bf16 v[10:13], v[160:163], v[208:211], v[10:13]
	v_mfma_f32_16x16x32_bf16 v[62:65], v[156:159], v[188:191], v[62:65]
	v_mfma_f32_16x16x32_bf16 v[58:61], v[164:167], v[188:191], v[58:61]
	v_mfma_f32_16x16x32_bf16 v[50:53], v[156:159], v[196:199], v[50:53]
	v_mfma_f32_16x16x32_bf16 v[42:45], v[164:167], v[196:199], v[42:45]
	v_mfma_f32_16x16x32_bf16 v[34:37], v[156:159], v[204:207], v[34:37]
	v_mfma_f32_16x16x32_bf16 v[26:29], v[164:167], v[204:207], v[26:29]
	v_mfma_f32_16x16x32_bf16 v[18:21], v[156:159], v[212:215], v[18:21]
	v_mfma_f32_16x16x32_bf16 v[10:13], v[164:167], v[212:215], v[10:13]
	v_mfma_f32_16x16x32_bf16 v[54:57], v[168:171], v[184:187], v[54:57]
	v_mfma_f32_16x16x32_bf16 v[46:49], v[176:179], v[184:187], v[46:49]
	v_mfma_f32_16x16x32_bf16 v[38:41], v[168:171], v[192:195], v[38:41]
	v_mfma_f32_16x16x32_bf16 v[30:33], v[176:179], v[192:195], v[30:33]
	v_mfma_f32_16x16x32_bf16 v[22:25], v[168:171], v[200:203], v[22:25]
	v_mfma_f32_16x16x32_bf16 v[14:17], v[176:179], v[200:203], v[14:17]
	v_mfma_f32_16x16x32_bf16 v[6:9], v[168:171], v[208:211], v[6:9]
	v_mfma_f32_16x16x32_bf16 v[2:5], v[176:179], v[208:211], v[2:5]
	v_mfma_f32_16x16x32_bf16 v[54:57], v[172:175], v[188:191], v[54:57]
	v_mfma_f32_16x16x32_bf16 v[46:49], v[180:183], v[188:191], v[46:49]
	v_mfma_f32_16x16x32_bf16 v[38:41], v[172:175], v[196:199], v[38:41]
	v_mfma_f32_16x16x32_bf16 v[30:33], v[180:183], v[196:199], v[30:33]
	v_mfma_f32_16x16x32_bf16 v[22:25], v[172:175], v[204:207], v[22:25]
	v_mfma_f32_16x16x32_bf16 v[14:17], v[180:183], v[204:207], v[14:17]
	v_mfma_f32_16x16x32_bf16 v[6:9], v[172:175], v[212:215], v[6:9]
	v_mfma_f32_16x16x32_bf16 v[2:5], v[180:183], v[212:215], v[2:5]
	s_barrier
; #define PG8_STAGE(bufoff, gbase, voff) do { _Pragma("unroll") for (int _i = 0; _i < 2; ++_i) \
;         __builtin_amdgcn_global_load_lds((const unsigned*)((const char*)(gbase) + (voff)[_i]), (PG8_LAS unsigned*)(lds + (bufoff) + ldsw + _i * 8192), 16, 0, 0); } while (0)
; #define PG8_LDA(dst, b, h) do { _Pragma("unroll") for (int m = 0; m < 4; ++m) _Pragma("unroll") for (int k = 0; k < 2; ++k) dst[m][k] = *(const PG8_LAS bf16x8*)(lds + PG8_SA(b, h) + aoff + m * 2048 + k * 1024); } while (0)
; #define PG8_LDB(dst, b, h) do { _Pragma("unroll") for (int n = 0; n < 2; ++n) _Pragma("unroll") for (int k = 0; k < 2; ++k) dst[n][k] = *(const PG8_LAS bf16x8*)(lds + PG8_SB(b, h) + boff + n * 2048 + k * 1024); } while (0)
; #define PG8_MMA(ai, bj, At, Bt) do { __builtin_amdgcn_s_setprio(1); _Pragma("unroll") for (int m = 0; m < 4; ++m) _Pragma("unroll") for (int n = 0; n < 2; ++n) _Pragma("unroll") for (int k = 0; k < 2; ++k) \
;         acc[ai][bj][m][n] = __builtin_amdgcn_mfma_f32_16x16x32_bf16(Bt[n][k], At[m][k], acc[ai][bj][m][n], 0, 0, 0); __builtin_amdgcn_s_setprio(0); } while (0)
; #define PG8_WAIT_V(n) asm volatile("s_waitcnt vmcnt(" #n ")" ::: "memory")
; #define PG8_WAIT_L(n) asm volatile("s_waitcnt lgkmcnt(" #n ")" ::: "memory")
; #define PG8_BAR __builtin_amdgcn_s_barrier()
; #define PG8_SCHED __builtin_amdgcn_sched_barrier(0)
; template <class Epi, class Sched, bool ALIGN_EPI = false, bool SP2 = false>
; __device__ __forceinline__ void gemm_phase(PG8_LAS unsigned char* lds, const Gemm g, const Sched& S, const Epi& E) {
;     ...
;             PG8_LDB(B0, 1, 0); PG8_LDB(B1, 1, 1); PG8_SCHED; PG8_LDA(At, 1, 0); PG8_STAGE(PG8_SA(0, 1), a2 + hstep, voffA);
;             PG8_WAIT_V(8); PG8_WAIT_L(0); PG8_BAR; PG8_MMA(0, 0, At, B0); PG8_MMA(0, 1, At, B1); PG8_BAR; PG8_SCHED;
;             PG8_LDA(At, 1, 1); PG8_STAGE(PG8_SB(1, 0), b3, voffB); PG8_STAGE(PG8_SB(1, 1), b3 + hstepB, voffB); PG8_STAGE(PG8_SA(1, 0), a3, voffA);
;             PG8_WAIT_V(8); PG8_WAIT_L(0); PG8_BAR; PG8_MMA(1, 0, At, B0); PG8_MMA(1, 1, At, B1); PG8_BAR; PG8_SCHED;
	s_add_i32 s76, 0, 0x18000
	v_add_u32_e32 v155, s76, v150
	s_add_i32 s77, 0, 0x1c000
	ds_read_b128 v[146:149], v155
	ds_read_b128 v[156:159], v155 offset:1024
	ds_read_b128 v[160:163], v155 offset:2048
	ds_read_b128 v[164:167], v155 offset:3072
	v_add_u32_e32 v155, s77, v150
	ds_read_b128 v[168:171], v155
	ds_read_b128 v[172:175], v155 offset:1024
	ds_read_b128 v[176:179], v155 offset:2048
	ds_read_b128 v[180:183], v155 offset:3072
	s_add_u32 s24, s24, 0x40000
	s_addc_u32 s25, s25, 0
	s_mov_b32 m0, s29
	ds_read_b128 v[184:187], v154 offset:32768
	ds_read_b128 v[188:191], v154 offset:33792
	ds_read_b128 v[192:195], v154 offset:34816
	ds_read_b128 v[196:199], v154 offset:35840
	ds_read_b128 v[200:203], v154 offset:36864
	ds_read_b128 v[204:207], v154 offset:37888
	ds_read_b128 v[208:211], v154 offset:38912
	ds_read_b128 v[212:215], v154 offset:39936
	global_load_lds_dwordx4 v130, s[24:25]
	s_mov_b32 m0, s30
	s_nop 0
	global_load_lds_dwordx4 v134, s[24:25]
	s_waitcnt vmcnt(8) lgkmcnt(0)
	s_barrier
	v_mfma_f32_16x16x32_bf16 v[126:129], v[146:149], v[184:187], v[126:129]
	v_mfma_f32_16x16x32_bf16 v[122:125], v[160:163], v[184:187], v[122:125]
	v_mfma_f32_16x16x32_bf16 v[114:117], v[146:149], v[192:195], v[114:117]
	v_mfma_f32_16x16x32_bf16 v[106:109], v[160:163], v[192:195], v[106:109]
	v_mfma_f32_16x16x32_bf16 v[98:101], v[146:149], v[200:203], v[98:101]
	v_mfma_f32_16x16x32_bf16 v[90:93], v[160:163], v[200:203], v[90:93]
	v_mfma_f32_16x16x32_bf16 v[82:85], v[146:149], v[208:211], v[82:85]
	v_mfma_f32_16x16x32_bf16 v[74:77], v[160:163], v[208:211], v[74:77]
	v_mfma_f32_16x16x32_bf16 v[126:129], v[156:159], v[188:191], v[126:129]
	v_mfma_f32_16x16x32_bf16 v[122:125], v[164:167], v[188:191], v[122:125]
	v_mfma_f32_16x16x32_bf16 v[114:117], v[156:159], v[196:199], v[114:117]
	v_mfma_f32_16x16x32_bf16 v[106:109], v[164:167], v[196:199], v[106:109]
	v_mfma_f32_16x16x32_bf16 v[98:101], v[156:159], v[204:207], v[98:101]
	v_mfma_f32_16x16x32_bf16 v[90:93], v[164:167], v[204:207], v[90:93]
	v_mfma_f32_16x16x32_bf16 v[82:85], v[156:159], v[212:215], v[82:85]
	v_mfma_f32_16x16x32_bf16 v[74:77], v[164:167], v[212:215], v[74:77]
	v_mfma_f32_16x16x32_bf16 v[118:121], v[168:171], v[184:187], v[118:121]
	v_mfma_f32_16x16x32_bf16 v[110:113], v[176:179], v[184:187], v[110:113]
	v_mfma_f32_16x16x32_bf16 v[102:105], v[168:171], v[192:195], v[102:105]
	v_mfma_f32_16x16x32_bf16 v[94:97], v[176:179], v[192:195], v[94:97]
	v_mfma_f32_16x16x32_bf16 v[86:89], v[168:171], v[200:203], v[86:89]
	v_mfma_f32_16x16x32_bf16 v[78:81], v[176:179], v[200:203], v[78:81]
	v_mfma_f32_16x16x32_bf16 v[70:73], v[168:171], v[208:211], v[70:73]
	v_mfma_f32_16x16x32_bf16 v[66:69], v[176:179], v[208:211], v[66:69]
	v_mfma_f32_16x16x32_bf16 v[118:121], v[172:175], v[188:191], v[118:121]
	v_mfma_f32_16x16x32_bf16 v[110:113], v[180:183], v[188:191], v[110:113]
	v_mfma_f32_16x16x32_bf16 v[102:105], v[172:175], v[196:199], v[102:105]
	v_mfma_f32_16x16x32_bf16 v[94:97], v[180:183], v[196:199], v[94:97]
	v_mfma_f32_16x16x32_bf16 v[86:89], v[172:175], v[204:207], v[86:89]
	v_mfma_f32_16x16x32_bf16 v[78:81], v[180:183], v[204:207], v[78:81]
	v_mfma_f32_16x16x32_bf16 v[70:73], v[172:175], v[212:215], v[70:73]
	v_mfma_f32_16x16x32_bf16 v[66:69], v[180:183], v[212:215], v[66:69]
	s_barrier
	s_add_i32 s24, s76, s26
	v_lshl_add_u64 v[216:217], v[216:217], 0, s[6:7]
	s_mov_b32 m0, s24
	ds_read_b128 v[184:187], v154 offset:49152
	ds_read_b128 v[188:191], v154 offset:50176
	ds_read_b128 v[192:195], v154 offset:51200
	ds_read_b128 v[196:199], v154 offset:52224
	ds_read_b128 v[200:203], v154 offset:53248
	ds_read_b128 v[204:207], v154 offset:54272
	ds_read_b128 v[208:211], v154 offset:55296
	ds_read_b128 v[212:215], v154 offset:56320
	global_load_lds_dwordx4 v[216:217], off
	s_add_i32 m0, s24, 0x2000
	s_add_u32 s22, s22, 0x10080
	v_lshl_add_u64 v[216:217], v[218:219], 0, s[6:7]
	s_addc_u32 s23, s23, 0
	s_add_i32 s24, s77, s26
	global_load_lds_dwordx4 v[216:217], off
	s_mov_b32 m0, s24
	s_nop 0
	global_load_lds_dwordx4 v132, s[22:23]
	s_add_i32 m0, s24, 0x2000
	s_nop 0
	global_load_lds_dwordx4 v136, s[22:23]
	v_lshl_add_u64 v[216:217], v[220:221], 0, s[6:7]
	s_mov_b32 m0, s33
	s_nop 0
	global_load_lds_dwordx4 v[216:217], off
	v_lshl_add_u64 v[216:217], v[222:223], 0, s[6:7]
	s_mov_b32 m0, s34
	s_nop 0
	global_load_lds_dwordx4 v[216:217], off
	s_waitcnt vmcnt(8) lgkmcnt(0)
	s_barrier
	v_mfma_f32_16x16x32_bf16 v[62:65], v[146:149], v[184:187], v[62:65]
	v_mfma_f32_16x16x32_bf16 v[58:61], v[160:163], v[184:187], v[58:61]
	v_mfma_f32_16x16x32_bf16 v[50:53], v[146:149], v[192:195], v[50:53]
	v_mfma_f32_16x16x32_bf16 v[42:45], v[160:163], v[192:195], v[42:45]
	v_mfma_f32_16x16x32_bf16 v[34:37], v[146:149], v[200:203], v[34:37]
	v_mfma_f32_16x16x32_bf16 v[26:29], v[160:163], v[200:203], v[26:29]
	v_mfma_f32_16x16x32_bf16 v[18:21], v[146:149], v[208:211], v[18:21]
	v_mfma_f32_16x16x32_bf16 v[10:13], v[160:163], v[208:211], v[10:13]
	v_mfma_f32_16x16x32_bf16 v[62:65], v[156:159], v[188:191], v[62:65]
	v_mfma_f32_16x16x32_bf16 v[58:61], v[164:167], v[188:191], v[58:61]
	v_mfma_f32_16x16x32_bf16 v[50:53], v[156:159], v[196:199], v[50:53]
	v_mfma_f32_16x16x32_bf16 v[42:45], v[164:167], v[196:199], v[42:45]
	v_mfma_f32_16x16x32_bf16 v[34:37], v[156:159], v[204:207], v[34:37]
	v_mfma_f32_16x16x32_bf16 v[26:29], v[164:167], v[204:207], v[26:29]
	v_mfma_f32_16x16x32_bf16 v[18:21], v[156:159], v[212:215], v[18:21]
	v_mfma_f32_16x16x32_bf16 v[10:13], v[164:167], v[212:215], v[10:13]
	v_mfma_f32_16x16x32_bf16 v[54:57], v[168:171], v[184:187], v[54:57]
	v_mfma_f32_16x16x32_bf16 v[46:49], v[176:179], v[184:187], v[46:49]
	v_mfma_f32_16x16x32_bf16 v[38:41], v[168:171], v[192:195], v[38:41]
	v_mfma_f32_16x16x32_bf16 v[30:33], v[176:179], v[192:195], v[30:33]
	v_mfma_f32_16x16x32_bf16 v[22:25], v[168:171], v[200:203], v[22:25]
	v_mfma_f32_16x16x32_bf16 v[14:17], v[176:179], v[200:203], v[14:17]
	v_mfma_f32_16x16x32_bf16 v[6:9], v[168:171], v[208:211], v[6:9]
	v_mfma_f32_16x16x32_bf16 v[2:5], v[176:179], v[208:211], v[2:5]
	v_mfma_f32_16x16x32_bf16 v[54:57], v[172:175], v[188:191], v[54:57]
	v_mfma_f32_16x16x32_bf16 v[46:49], v[180:183], v[188:191], v[46:49]
	v_mfma_f32_16x16x32_bf16 v[38:41], v[172:175], v[196:199], v[38:41]
	v_mfma_f32_16x16x32_bf16 v[30:33], v[180:183], v[196:199], v[30:33]
	v_mfma_f32_16x16x32_bf16 v[22:25], v[172:175], v[204:207], v[22:25]
	v_mfma_f32_16x16x32_bf16 v[14:17], v[180:183], v[204:207], v[14:17]
	v_mfma_f32_16x16x32_bf16 v[6:9], v[172:175], v[212:215], v[6:9]
	v_mfma_f32_16x16x32_bf16 v[2:5], v[180:183], v[212:215], v[2:5]
	s_barrier
	s_add_i32 s75, s75, 2
	s_add_u32 s20, s20, 0x100
	s_addc_u32 s21, s21, 0
	s_add_u32 s73, s73, 0x100
	s_addc_u32 s74, s74, 0
	s_cmp_gt_u32 s75, 13
	s_cbranch_scc0 .LBB0_192

; #define PG8_STAGE(bufoff, gbase, voff) do { _Pragma("unroll") for (int _i = 0; _i < 2; ++_i) \
;         __builtin_amdgcn_global_load_lds((const unsigned*)((const char*)(gbase) + (voff)[_i]), (PG8_LAS unsigned*)(lds + (bufoff) + ldsw + _i * 8192), 16, 0, 0); } while (0)
; #define PG8_LDA(dst, b, h) do { _Pragma("unroll") for (int m = 0; m < 4; ++m) _Pragma("unroll") for (int k = 0; k < 2; ++k) dst[m][k] = *(const PG8_LAS bf16x8*)(lds + PG8_SA(b, h) + aoff + m * 2048 + k * 1024); } while (0)
; #define PG8_LDB(dst, b, h) do { _Pragma("unroll") for (int n = 0; n < 2; ++n) _Pragma("unroll") for (int k = 0; k < 2; ++k) dst[n][k] = *(const PG8_LAS bf16x8*)(lds + PG8_SB(b, h) + boff + n * 2048 + k * 1024); } while (0)
; #define PG8_WAIT_V(n) asm volatile("s_waitcnt vmcnt(" #n ")" ::: "memory")
; #define PG8_WAIT_L(n) asm volatile("s_waitcnt lgkmcnt(" #n ")" ::: "memory")
; #define PG8_BAR __builtin_amdgcn_s_barrier()
; #define PG8_SCHED __builtin_amdgcn_sched_barrier(0)
; template <class Epi, class Sched, bool ALIGN_EPI = false, bool SP2 = false>
; __device__ __forceinline__ void gemm_phase(PG8_LAS unsigned char* lds, const Gemm g, const Sched& S, const Epi& E) {
;     ...
;         const bool has_next = S.next(ui + 1, nxt);
;         const char* nA = has_next ? (const char*)g.A + (size_t)nxt.pm * tstep : cA; const char* nB = has_next ? (const char*)g.Bt + (size_t)nxt.pn * tstep : cB;
;         for (int t = 0; t < nt; t += 2) {
;             if constexpr (Epi::HAS_MID) { if (t == nt / 2) E.mid(acc, cur, wr, wc, fr, fq); }
;             const bool last = (t == nt - 2);
;             const char* a1 = cA + (size_t)(t + 1) * kstep;
;             const char* a2 = last ? nA : cA + (size_t)(t + 2) * kstep; const char* b2 = last ? nB : cB + (size_t)(t + 2) * kstep;
;             const char* a3 = a2 + kstep; const char* b3 = b2 + kstep;
;             if (last && has_next) S.a_ready(nxt);
;             if constexpr (SP2) {
;             PG8_LDB(B0, 0, 0); PG8_LDB(B1, 0, 1); PG8_SCHED; PG8_LDA(At, 0, 0); PG8_STAGE(PG8_SA(1, 1), a1 + hstep, voffA);
;             PG8_WAIT_V(8); PG8_WAIT_L(0); PG8_BAR; PG8_MMA(0, 0, At, B0); PG8_MMA(0, 1, At, B1); PG8_BAR; PG8_SCHED;
;             PG8_LDA(At, 0, 1); PG8_STAGE(PG8_SB(0, 0), b2, voffB); PG8_STAGE(PG8_SB(0, 1), b2 + hstepB, voffB); PG8_STAGE(PG8_SA(0, 0), a2, voffA);
.LBB0_1312:
	s_ashr_i32 s27, s26, 31
	s_lshl_b64 s[28:29], s[26:27], 19
	s_add_u32 s28, s12, s28
	s_addc_u32 s29, s13, s29
	s_and_b64 s[34:35], s[6:7], exec
	s_cselect_b32 s9, s29, s39
	s_cselect_b32 s27, s28, s38
	s_ashr_i32 s25, s24, 31
	s_lshl_b64 s[34:35], s[24:25], 19
	s_add_u32 s34, s78, s34
	s_addc_u32 s35, s79, s35
	s_and_b64 s[42:43], s[6:7], exec
	s_cselect_b32 s25, s35, s41
	s_cselect_b32 s37, s34, s40
	s_add_u32 s38, s38, 0x40080
	s_addc_u32 s39, s39, 0
	s_add_u32 s59, s40, 0x100
	s_addc_u32 s60, s41, 0
	s_mov_b32 s61, -2
	ds_read_b128 v[146:149], v154
	ds_read_b128 v[158:161], v154 offset:1024
	ds_read_b128 v[162:165], v154 offset:2048
	ds_read_b128 v[166:169], v154 offset:3072
	ds_read_b128 v[170:173], v155
	ds_read_b128 v[174:177], v155 offset:1024
	ds_read_b128 v[178:181], v155 offset:2048
	ds_read_b128 v[182:185], v155 offset:3072
	s_add_u32 s40, s38, 0xfffc0080
	s_addc_u32 s41, s39, -1
	s_cmp_eq_u32 s61, 12
	s_cselect_b32 s43, s9, s41
	s_cselect_b32 s42, s27, s40
	s_cselect_b32 s41, s25, s60
	s_cselect_b32 s40, s37, s59
	s_add_i32 m0, s31, 0xc000
	ds_read_b128 v[186:189], v156
	ds_read_b128 v[190:193], v156 offset:1024
	ds_read_b128 v[194:197], v156 offset:2048
	ds_read_b128 v[198:201], v156 offset:3072
	ds_read_b128 v[202:205], v156 offset:4096
	ds_read_b128 v[206:209], v156 offset:5120
	ds_read_b128 v[210:213], v156 offset:6144
	ds_read_b128 v[214:217], v156 offset:7168
	global_load_lds_dwordx4 v138, s[38:39]
	s_add_i32 m0, s31, 0xe000
	s_nop 0
	global_load_lds_dwordx4 v140, s[38:39]
	s_waitcnt vmcnt(8) lgkmcnt(0)
	s_barrier
	v_mfma_f32_16x16x32_bf16 v[126:129], v[146:149], v[186:189], 0
	v_mfma_f32_16x16x32_bf16 v[122:125], v[162:165], v[186:189], 0
	v_mfma_f32_16x16x32_bf16 v[110:113], v[146:149], v[194:197], 0
	v_mfma_f32_16x16x32_bf16 v[106:109], v[162:165], v[194:197], 0
	v_mfma_f32_16x16x32_bf16 v[94:97], v[146:149], v[202:205], 0
	v_mfma_f32_16x16x32_bf16 v[90:93], v[162:165], v[202:205], 0
	v_mfma_f32_16x16x32_bf16 v[78:81], v[146:149], v[210:213], 0
	v_mfma_f32_16x16x32_bf16 v[74:77], v[162:165], v[210:213], 0
	v_mfma_f32_16x16x32_bf16 v[126:129], v[158:161], v[190:193], v[126:129]
	v_mfma_f32_16x16x32_bf16 v[122:125], v[166:169], v[190:193], v[122:125]
	v_mfma_f32_16x16x32_bf16 v[110:113], v[158:161], v[198:201], v[110:113]
	v_mfma_f32_16x16x32_bf16 v[106:109], v[166:169], v[198:201], v[106:109]
	v_mfma_f32_16x16x32_bf16 v[94:97], v[158:161], v[206:209], v[94:97]
	v_mfma_f32_16x16x32_bf16 v[90:93], v[166:169], v[206:209], v[90:93]
	v_mfma_f32_16x16x32_bf16 v[78:81], v[158:161], v[214:217], v[78:81]
	v_mfma_f32_16x16x32_bf16 v[74:77], v[166:169], v[214:217], v[74:77]
	v_mfma_f32_16x16x32_bf16 v[118:121], v[170:173], v[186:189], 0
	v_mfma_f32_16x16x32_bf16 v[114:117], v[178:181], v[186:189], 0
	v_mfma_f32_16x16x32_bf16 v[102:105], v[170:173], v[194:197], 0
	v_mfma_f32_16x16x32_bf16 v[98:101], v[178:181], v[194:197], 0
	v_mfma_f32_16x16x32_bf16 v[86:89], v[170:173], v[202:205], 0
	v_mfma_f32_16x16x32_bf16 v[82:85], v[178:181], v[202:205], 0
	v_mfma_f32_16x16x32_bf16 v[70:73], v[170:173], v[210:213], 0
	v_mfma_f32_16x16x32_bf16 v[66:69], v[178:181], v[210:213], 0
	v_mfma_f32_16x16x32_bf16 v[118:121], v[174:177], v[190:193], v[118:121]
	v_mfma_f32_16x16x32_bf16 v[114:117], v[182:185], v[190:193], v[114:117]
	v_mfma_f32_16x16x32_bf16 v[102:105], v[174:177], v[198:201], v[102:105]
	v_mfma_f32_16x16x32_bf16 v[98:101], v[182:185], v[198:201], v[98:101]
	v_mfma_f32_16x16x32_bf16 v[86:89], v[174:177], v[206:209], v[86:89]
	v_mfma_f32_16x16x32_bf16 v[82:85], v[182:185], v[206:209], v[82:85]
	v_mfma_f32_16x16x32_bf16 v[70:73], v[174:177], v[214:217], v[70:73]
	v_mfma_f32_16x16x32_bf16 v[66:69], v[182:185], v[214:217], v[66:69]
	s_barrier
	s_add_i32 s62, s57, s30
	v_lshl_add_u64 v[150:151], s[40:41], 0, v[132:133]
	s_mov_b32 m0, s62
	ds_read_b128 v[186:189], v156 offset:16384
	ds_read_b128 v[190:193], v156 offset:17408
	ds_read_b128 v[194:197], v156 offset:18432
	ds_read_b128 v[198:201], v156 offset:19456
	ds_read_b128 v[202:205], v156 offset:20480
	ds_read_b128 v[206:209], v156 offset:21504
	ds_read_b128 v[210:213], v156 offset:22528
	ds_read_b128 v[214:217], v156 offset:23552
	global_load_lds_dwordx4 v132, s[40:41]
	s_add_i32 m0, s62, 0x2000
	s_add_u32 s62, s40, 0x10000
	v_lshl_add_u64 v[218:219], s[40:41], 0, v[136:137]
	s_addc_u32 s63, s41, 0
	s_add_i32 s64, s58, s30
	global_load_lds_dwordx4 v136, s[40:41]
	s_mov_b32 m0, s64
	v_lshl_add_u64 v[222:223], s[42:43], 0, v[134:135]
	global_load_lds_dwordx4 v132, s[62:63]
	s_add_i32 m0, s64, 0x2000
	s_nop 0
	global_load_lds_dwordx4 v136, s[62:63]
	v_lshl_add_u64 v[220:221], s[42:43], 0, v[130:131]
	s_mov_b32 m0, s31
	s_nop 0
	global_load_lds_dwordx4 v130, s[42:43]
	s_mov_b32 m0, s33
	s_nop 0
	global_load_lds_dwordx4 v134, s[42:43]
	s_waitcnt vmcnt(8) lgkmcnt(0)
	s_barrier
; #define PG8_STAGE(bufoff, gbase, voff) do { _Pragma("unroll") for (int _i = 0; _i < 2; ++_i) \
;         __builtin_amdgcn_global_load_lds((const unsigned*)((const char*)(gbase) + (voff)[_i]), (PG8_LAS unsigned*)(lds + (bufoff) + ldsw + _i * 8192), 16, 0, 0); } while (0)
; #define PG8_LDA(dst, b, h) do { _Pragma("unroll") for (int m = 0; m < 4; ++m) _Pragma("unroll") for (int k = 0; k < 2; ++k) dst[m][k] = *(const PG8_LAS bf16x8*)(lds + PG8_SA(b, h) + aoff + m * 2048 + k * 1024); } while (0)
; #define PG8_LDB(dst, b, h) do { _Pragma("unroll") for (int n = 0; n < 2; ++n) _Pragma("unroll") for (int k = 0; k < 2; ++k) dst[n][k] = *(const PG8_LAS bf16x8*)(lds + PG8_SB(b, h) + boff + n * 2048 + k * 1024); } while (0)
; #define PG8_MMA(ai, bj, At, Bt) do { __builtin_amdgcn_s_setprio(1); _Pragma("unroll") for (int m = 0; m < 4; ++m) _Pragma("unroll") for (int n = 0; n < 2; ++n) _Pragma("unroll") for (int k = 0; k < 2; ++k) \
;         acc[ai][bj][m][n] = __builtin_amdgcn_mfma_f32_16x16x32_bf16(Bt[n][k], At[m][k], acc[ai][bj][m][n], 0, 0, 0); __builtin_amdgcn_s_setprio(0); } while (0)
; #define PG8_WAIT_V(n) asm volatile("s_waitcnt vmcnt(" #n ")" ::: "memory")
; #define PG8_WAIT_L(n) asm volatile("s_waitcnt lgkmcnt(" #n ")" ::: "memory")
; #define PG8_BAR __builtin_amdgcn_s_barrier()
; #define PG8_SCHED __builtin_amdgcn_sched_barrier(0)
; template <class Epi, class Sched, bool ALIGN_EPI = false, bool SP2 = false>
; __device__ __forceinline__ void gemm_phase(PG8_LAS unsigned char* lds, const Gemm g, const Sched& S, const Epi& E) {
;     ...
;             PG8_WAIT_V(8); PG8_WAIT_L(0); PG8_BAR; PG8_MMA(1, 0, At, B0); PG8_MMA(1, 1, At, B1); PG8_BAR; PG8_SCHED;
;             PG8_LDB(B0, 1, 0); PG8_LDB(B1, 1, 1); PG8_SCHED; PG8_LDA(At, 1, 0); PG8_STAGE(PG8_SA(0, 1), a2 + hstep, voffA);
;             PG8_WAIT_V(8); PG8_WAIT_L(0); PG8_BAR; PG8_MMA(0, 0, At, B0); PG8_MMA(0, 1, At, B1); PG8_BAR; PG8_SCHED;
	v_mfma_f32_16x16x32_bf16 v[62:65], v[146:149], v[186:189], 0
	v_mfma_f32_16x16x32_bf16 v[58:61], v[162:165], v[186:189], 0
	v_mfma_f32_16x16x32_bf16 v[46:49], v[146:149], v[194:197], 0
	v_mfma_f32_16x16x32_bf16 v[42:45], v[162:165], v[194:197], 0
	v_mfma_f32_16x16x32_bf16 v[30:33], v[146:149], v[202:205], 0
	v_mfma_f32_16x16x32_bf16 v[26:29], v[162:165], v[202:205], 0
	v_mfma_f32_16x16x32_bf16 v[14:17], v[146:149], v[210:213], 0
	v_mfma_f32_16x16x32_bf16 v[10:13], v[162:165], v[210:213], 0
	v_mfma_f32_16x16x32_bf16 v[62:65], v[158:161], v[190:193], v[62:65]
	v_mfma_f32_16x16x32_bf16 v[58:61], v[166:169], v[190:193], v[58:61]
	v_mfma_f32_16x16x32_bf16 v[46:49], v[158:161], v[198:201], v[46:49]
	v_mfma_f32_16x16x32_bf16 v[42:45], v[166:169], v[198:201], v[42:45]
	v_mfma_f32_16x16x32_bf16 v[30:33], v[158:161], v[206:209], v[30:33]
	v_mfma_f32_16x16x32_bf16 v[26:29], v[166:169], v[206:209], v[26:29]
	v_mfma_f32_16x16x32_bf16 v[14:17], v[158:161], v[214:217], v[14:17]
	v_mfma_f32_16x16x32_bf16 v[10:13], v[166:169], v[214:217], v[10:13]
	v_mfma_f32_16x16x32_bf16 v[54:57], v[170:173], v[186:189], 0
	v_mfma_f32_16x16x32_bf16 v[50:53], v[178:181], v[186:189], 0
	v_mfma_f32_16x16x32_bf16 v[38:41], v[170:173], v[194:197], 0
	v_mfma_f32_16x16x32_bf16 v[34:37], v[178:181], v[194:197], 0
	v_mfma_f32_16x16x32_bf16 v[22:25], v[170:173], v[202:205], 0
	v_mfma_f32_16x16x32_bf16 v[18:21], v[178:181], v[202:205], 0
	v_mfma_f32_16x16x32_bf16 v[6:9], v[170:173], v[210:213], 0
	v_mfma_f32_16x16x32_bf16 v[2:5], v[178:181], v[210:213], 0
	v_mfma_f32_16x16x32_bf16 v[54:57], v[174:177], v[190:193], v[54:57]
	v_mfma_f32_16x16x32_bf16 v[50:53], v[182:185], v[190:193], v[50:53]
	v_mfma_f32_16x16x32_bf16 v[38:41], v[174:177], v[198:201], v[38:41]
	v_mfma_f32_16x16x32_bf16 v[34:37], v[182:185], v[198:201], v[34:37]
	v_mfma_f32_16x16x32_bf16 v[22:25], v[174:177], v[206:209], v[22:25]
	v_mfma_f32_16x16x32_bf16 v[18:21], v[182:185], v[206:209], v[18:21]
	v_mfma_f32_16x16x32_bf16 v[6:9], v[174:177], v[214:217], v[6:9]
	v_mfma_f32_16x16x32_bf16 v[2:5], v[182:185], v[214:217], v[2:5]
	s_barrier
	s_add_i32 s62, 0, 0x18000
	v_add_u32_e32 v157, s62, v152
	s_add_i32 s63, 0, 0x1c000
	ds_read_b128 v[146:149], v157
	ds_read_b128 v[158:161], v157 offset:1024
	ds_read_b128 v[162:165], v157 offset:2048
	ds_read_b128 v[166:169], v157 offset:3072
	v_add_u32_e32 v157, s63, v152
	ds_read_b128 v[170:173], v157
	ds_read_b128 v[174:177], v157 offset:1024
	ds_read_b128 v[178:181], v157 offset:2048
	ds_read_b128 v[182:185], v157 offset:3072
	s_add_u32 s42, s42, 0x40000
	s_addc_u32 s43, s43, 0
	s_mov_b32 m0, s44
	ds_read_b128 v[186:189], v156 offset:32768
	ds_read_b128 v[190:193], v156 offset:33792
	ds_read_b128 v[194:197], v156 offset:34816
	ds_read_b128 v[198:201], v156 offset:35840
	ds_read_b128 v[202:205], v156 offset:36864
	ds_read_b128 v[206:209], v156 offset:37888
	ds_read_b128 v[210:213], v156 offset:38912
	ds_read_b128 v[214:217], v156 offset:39936
	global_load_lds_dwordx4 v130, s[42:43]
	s_mov_b32 m0, s45
	s_nop 0
	global_load_lds_dwordx4 v134, s[42:43]
	s_waitcnt vmcnt(8) lgkmcnt(0)
	s_barrier
	v_mfma_f32_16x16x32_bf16 v[126:129], v[146:149], v[186:189], v[126:129]
	v_mfma_f32_16x16x32_bf16 v[122:125], v[162:165], v[186:189], v[122:125]
	v_mfma_f32_16x16x32_bf16 v[110:113], v[146:149], v[194:197], v[110:113]
	v_mfma_f32_16x16x32_bf16 v[106:109], v[162:165], v[194:197], v[106:109]
	v_mfma_f32_16x16x32_bf16 v[94:97], v[146:149], v[202:205], v[94:97]
	v_mfma_f32_16x16x32_bf16 v[90:93], v[162:165], v[202:205], v[90:93]
	v_mfma_f32_16x16x32_bf16 v[78:81], v[146:149], v[210:213], v[78:81]
	v_mfma_f32_16x16x32_bf16 v[74:77], v[162:165], v[210:213], v[74:77]
	v_mfma_f32_16x16x32_bf16 v[126:129], v[158:161], v[190:193], v[126:129]
	v_mfma_f32_16x16x32_bf16 v[122:125], v[166:169], v[190:193], v[122:125]
	v_mfma_f32_16x16x32_bf16 v[110:113], v[158:161], v[198:201], v[110:113]
	v_mfma_f32_16x16x32_bf16 v[106:109], v[166:169], v[198:201], v[106:109]
	v_mfma_f32_16x16x32_bf16 v[94:97], v[158:161], v[206:209], v[94:97]
	v_mfma_f32_16x16x32_bf16 v[90:93], v[166:169], v[206:209], v[90:93]
	v_mfma_f32_16x16x32_bf16 v[78:81], v[158:161], v[214:217], v[78:81]
	v_mfma_f32_16x16x32_bf16 v[74:77], v[166:169], v[214:217], v[74:77]
	v_mfma_f32_16x16x32_bf16 v[118:121], v[170:173], v[186:189], v[118:121]
	v_mfma_f32_16x16x32_bf16 v[114:117], v[178:181], v[186:189], v[114:117]
	v_mfma_f32_16x16x32_bf16 v[102:105], v[170:173], v[194:197], v[102:105]
	v_mfma_f32_16x16x32_bf16 v[98:101], v[178:181], v[194:197], v[98:101]
	v_mfma_f32_16x16x32_bf16 v[86:89], v[170:173], v[202:205], v[86:89]
	v_mfma_f32_16x16x32_bf16 v[82:85], v[178:181], v[202:205], v[82:85]
	v_mfma_f32_16x16x32_bf16 v[70:73], v[170:173], v[210:213], v[70:73]
	v_mfma_f32_16x16x32_bf16 v[66:69], v[178:181], v[210:213], v[66:69]
	v_mfma_f32_16x16x32_bf16 v[118:121], v[174:177], v[190:193], v[118:121]
	v_mfma_f32_16x16x32_bf16 v[114:117], v[182:185], v[190:193], v[114:117]
	v_mfma_f32_16x16x32_bf16 v[102:105], v[174:177], v[198:201], v[102:105]
	v_mfma_f32_16x16x32_bf16 v[98:101], v[182:185], v[198:201], v[98:101]
	v_mfma_f32_16x16x32_bf16 v[86:89], v[174:177], v[206:209], v[86:89]
	v_mfma_f32_16x16x32_bf16 v[82:85], v[182:185], v[206:209], v[82:85]
	v_mfma_f32_16x16x32_bf16 v[70:73], v[174:177], v[214:217], v[70:73]
	v_mfma_f32_16x16x32_bf16 v[66:69], v[182:185], v[214:217], v[66:69]
	s_barrier
; #define PG8_STAGE(bufoff, gbase, voff) do { _Pragma("unroll") for (int _i = 0; _i < 2; ++_i) \
;         __builtin_amdgcn_global_load_lds((const unsigned*)((const char*)(gbase) + (voff)[_i]), (PG8_LAS unsigned*)(lds + (bufoff) + ldsw + _i * 8192), 16, 0, 0); } while (0)
; #define PG8_LDA(dst, b, h) do { _Pragma("unroll") for (int m = 0; m < 4; ++m) _Pragma("unroll") for (int k = 0; k < 2; ++k) dst[m][k] = *(const PG8_LAS bf16x8*)(lds + PG8_SA(b, h) + aoff + m * 2048 + k * 1024); } while (0)
; #define PG8_LDB(dst, b, h) do { _Pragma("unroll") for (int n = 0; n < 2; ++n) _Pragma("unroll") for (int k = 0; k < 2; ++k) dst[n][k] = *(const PG8_LAS bf16x8*)(lds + PG8_SB(b, h) + boff + n * 2048 + k * 1024); } while (0)
; #define PG8_MMA(ai, bj, At, Bt) do { __builtin_amdgcn_s_setprio(1); _Pragma("unroll") for (int m = 0; m < 4; ++m) _Pragma("unroll") for (int n = 0; n < 2; ++n) _Pragma("unroll") for (int k = 0; k < 2; ++k) \
;         acc[ai][bj][m][n] = __builtin_amdgcn_mfma_f32_16x16x32_bf16(Bt[n][k], At[m][k], acc[ai][bj][m][n], 0, 0, 0); __builtin_amdgcn_s_setprio(0); } while (0)
; #define PG8_WAIT_V(n) asm volatile("s_waitcnt vmcnt(" #n ")" ::: "memory")
; #define PG8_WAIT_L(n) asm volatile("s_waitcnt lgkmcnt(" #n ")" ::: "memory")
; template <class Epi, class Sched, bool ALIGN_EPI = false, bool SP2 = false>
; __device__ __forceinline__ void gemm_phase(PG8_LAS unsigned char* lds, const Gemm g, const Sched& S, const Epi& E) {
;     ...
;             const bool last = (t == nt - 2);
;             const char* a1 = cA + (size_t)(t + 1) * kstep;
;             const char* a2 = last ? nA : cA + (size_t)(t + 2) * kstep; const char* b2 = last ? nB : cB + (size_t)(t + 2) * kstep;
;             const char* a3 = a2 + kstep; const char* b3 = b2 + kstep;
;             if (last && has_next) S.a_ready(nxt);
;             if constexpr (SP2) {
;             PG8_LDB(B0, 0, 0); PG8_LDB(B1, 0, 1); PG8_SCHED; PG8_LDA(At, 0, 0); PG8_STAGE(PG8_SA(1, 1), a1 + hstep, voffA);
;             PG8_WAIT_V(8); PG8_WAIT_L(0); PG8_BAR; PG8_MMA(0, 0, At, B0); PG8_MMA(0, 1, At, B1); PG8_BAR; PG8_SCHED;
;     ...
;             PG8_LDA(At, 1, 1); PG8_STAGE(PG8_SB(1, 0), b3, voffB); PG8_STAGE(PG8_SB(1, 1), b3 + hstepB, voffB); PG8_STAGE(PG8_SA(1, 0), a3, voffA);
;             PG8_WAIT_V(8); PG8_WAIT_L(0); PG8_BAR; PG8_MMA(1, 0, At, B0); PG8_MMA(1, 1, At, B1); PG8_BAR; PG8_SCHED;
	s_add_i32 s42, s62, s30
	v_lshl_add_u64 v[150:151], v[150:151], 0, s[10:11]
	s_mov_b32 m0, s42
	ds_read_b128 v[186:189], v156 offset:49152
	ds_read_b128 v[190:193], v156 offset:50176
	ds_read_b128 v[194:197], v156 offset:51200
	ds_read_b128 v[198:201], v156 offset:52224
	ds_read_b128 v[202:205], v156 offset:53248
	ds_read_b128 v[206:209], v156 offset:54272
	ds_read_b128 v[210:213], v156 offset:55296
	ds_read_b128 v[214:217], v156 offset:56320
	global_load_lds_dwordx4 v[150:151], off
	s_add_i32 m0, s42, 0x2000
	s_add_u32 s40, s40, 0x10080
	v_lshl_add_u64 v[150:151], v[218:219], 0, s[10:11]
	s_addc_u32 s41, s41, 0
	s_add_i32 s42, s63, s30
	global_load_lds_dwordx4 v[150:151], off
	s_mov_b32 m0, s42
	s_nop 0
	global_load_lds_dwordx4 v132, s[40:41]
	s_add_i32 m0, s42, 0x2000
	s_nop 0
	global_load_lds_dwordx4 v136, s[40:41]
	v_lshl_add_u64 v[150:151], v[220:221], 0, s[10:11]
	s_mov_b32 m0, s47
	s_nop 0
	global_load_lds_dwordx4 v[150:151], off
	v_lshl_add_u64 v[150:151], v[222:223], 0, s[10:11]
	s_mov_b32 m0, s54
	s_nop 0
	global_load_lds_dwordx4 v[150:151], off
	s_waitcnt vmcnt(8) lgkmcnt(0)
	s_barrier
	v_mfma_f32_16x16x32_bf16 v[62:65], v[146:149], v[186:189], v[62:65]
	v_mfma_f32_16x16x32_bf16 v[58:61], v[162:165], v[186:189], v[58:61]
	v_mfma_f32_16x16x32_bf16 v[46:49], v[146:149], v[194:197], v[46:49]
	v_mfma_f32_16x16x32_bf16 v[42:45], v[162:165], v[194:197], v[42:45]
	v_mfma_f32_16x16x32_bf16 v[30:33], v[146:149], v[202:205], v[30:33]
	v_mfma_f32_16x16x32_bf16 v[26:29], v[162:165], v[202:205], v[26:29]
	v_mfma_f32_16x16x32_bf16 v[14:17], v[146:149], v[210:213], v[14:17]
	v_mfma_f32_16x16x32_bf16 v[10:13], v[162:165], v[210:213], v[10:13]
	v_mfma_f32_16x16x32_bf16 v[62:65], v[158:161], v[190:193], v[62:65]
	v_mfma_f32_16x16x32_bf16 v[58:61], v[166:169], v[190:193], v[58:61]
	v_mfma_f32_16x16x32_bf16 v[46:49], v[158:161], v[198:201], v[46:49]
	v_mfma_f32_16x16x32_bf16 v[42:45], v[166:169], v[198:201], v[42:45]
	v_mfma_f32_16x16x32_bf16 v[30:33], v[158:161], v[206:209], v[30:33]
	v_mfma_f32_16x16x32_bf16 v[26:29], v[166:169], v[206:209], v[26:29]
	v_mfma_f32_16x16x32_bf16 v[14:17], v[158:161], v[214:217], v[14:17]
	v_mfma_f32_16x16x32_bf16 v[10:13], v[166:169], v[214:217], v[10:13]
	v_mfma_f32_16x16x32_bf16 v[54:57], v[170:173], v[186:189], v[54:57]
	v_mfma_f32_16x16x32_bf16 v[50:53], v[178:181], v[186:189], v[50:53]
	v_mfma_f32_16x16x32_bf16 v[38:41], v[170:173], v[194:197], v[38:41]
	v_mfma_f32_16x16x32_bf16 v[34:37], v[178:181], v[194:197], v[34:37]
	v_mfma_f32_16x16x32_bf16 v[22:25], v[170:173], v[202:205], v[22:25]
	v_mfma_f32_16x16x32_bf16 v[18:21], v[178:181], v[202:205], v[18:21]
	v_mfma_f32_16x16x32_bf16 v[6:9], v[170:173], v[210:213], v[6:9]
	v_mfma_f32_16x16x32_bf16 v[2:5], v[178:181], v[210:213], v[2:5]
	v_mfma_f32_16x16x32_bf16 v[54:57], v[174:177], v[190:193], v[54:57]
	v_mfma_f32_16x16x32_bf16 v[50:53], v[182:185], v[190:193], v[50:53]
	v_mfma_f32_16x16x32_bf16 v[38:41], v[174:177], v[198:201], v[38:41]
	v_mfma_f32_16x16x32_bf16 v[34:37], v[182:185], v[198:201], v[34:37]
	v_mfma_f32_16x16x32_bf16 v[22:25], v[174:177], v[206:209], v[22:25]
	v_mfma_f32_16x16x32_bf16 v[18:21], v[182:185], v[206:209], v[18:21]
	v_mfma_f32_16x16x32_bf16 v[6:9], v[174:177], v[214:217], v[6:9]
	v_mfma_f32_16x16x32_bf16 v[2:5], v[182:185], v[214:217], v[2:5]
	s_barrier
	s_add_i32 s61, s61, 2
	s_add_u32 s38, s38, 0x100
	s_addc_u32 s39, s39, 0
	s_add_u32 s59, s59, 0x100
	s_addc_u32 s60, s60, 0
	s_cmp_gt_u32 s61, 13
	s_cbranch_scc1 .Lpp1_x
.LBB0_1313:
	ds_read_b128 v[146:149], v154
	ds_read_b128 v[158:161], v154 offset:1024
	ds_read_b128 v[162:165], v154 offset:2048
	ds_read_b128 v[166:169], v154 offset:3072
	ds_read_b128 v[170:173], v155
	ds_read_b128 v[174:177], v155 offset:1024
	ds_read_b128 v[178:181], v155 offset:2048
	ds_read_b128 v[182:185], v155 offset:3072
	s_add_u32 s40, s38, 0xfffc0080
	s_addc_u32 s41, s39, -1
	s_cmp_eq_u32 s61, 12
	s_cselect_b32 s43, s9, s41
	s_cselect_b32 s42, s27, s40
	s_cselect_b32 s41, s25, s60
	s_cselect_b32 s40, s37, s59
	s_add_i32 m0, s31, 0xc000
	ds_read_b128 v[186:189], v156
	ds_read_b128 v[190:193], v156 offset:1024
	ds_read_b128 v[194:197], v156 offset:2048
	ds_read_b128 v[198:201], v156 offset:3072
	ds_read_b128 v[202:205], v156 offset:4096
	ds_read_b128 v[206:209], v156 offset:5120
	ds_read_b128 v[210:213], v156 offset:6144
	ds_read_b128 v[214:217], v156 offset:7168
	global_load_lds_dwordx4 v138, s[38:39]
	s_add_i32 m0, s31, 0xe000
	s_nop 0
	global_load_lds_dwordx4 v140, s[38:39]
	s_waitcnt vmcnt(8) lgkmcnt(0)
	s_barrier
; #define PG8_STAGE(bufoff, gbase, voff) do { _Pragma("unroll") for (int _i = 0; _i < 2; ++_i) \
;         __builtin_amdgcn_global_load_lds((const unsigned*)((const char*)(gbase) + (voff)[_i]), (PG8_LAS unsigned*)(lds + (bufoff) + ldsw + _i * 8192), 16, 0, 0); } while (0)
; #define PG8_LDA(dst, b, h) do { _Pragma("unroll") for (int m = 0; m < 4; ++m) _Pragma("unroll") for (int k = 0; k < 2; ++k) dst[m][k] = *(const PG8_LAS bf16x8*)(lds + PG8_SA(b, h) + aoff + m * 2048 + k * 1024); } while (0)
; #define PG8_MMA(ai, bj, At, Bt) do { __builtin_amdgcn_s_setprio(1); _Pragma("unroll") for (int m = 0; m < 4; ++m) _Pragma("unroll") for (int n = 0; n < 2; ++n) _Pragma("unroll") for (int k = 0; k < 2; ++k) \
;         acc[ai][bj][m][n] = __builtin_amdgcn_mfma_f32_16x16x32_bf16(Bt[n][k], At[m][k], acc[ai][bj][m][n], 0, 0, 0); __builtin_amdgcn_s_setprio(0); } while (0)
; #define PG8_WAIT_V(n) asm volatile("s_waitcnt vmcnt(" #n ")" ::: "memory")
; #define PG8_WAIT_L(n) asm volatile("s_waitcnt lgkmcnt(" #n ")" ::: "memory")
; #define PG8_BAR __builtin_amdgcn_s_barrier()
; #define PG8_SCHED __builtin_amdgcn_sched_barrier(0)
; template <class Epi, class Sched, bool ALIGN_EPI = false, bool SP2 = false>
; __device__ __forceinline__ void gemm_phase(PG8_LAS unsigned char* lds, const Gemm g, const Sched& S, const Epi& E) {
;     ...
;             PG8_WAIT_V(8); PG8_WAIT_L(0); PG8_BAR; PG8_MMA(0, 0, At, B0); PG8_MMA(0, 1, At, B1); PG8_BAR; PG8_SCHED;
;             PG8_LDA(At, 0, 1); PG8_STAGE(PG8_SB(0, 0), b2, voffB); PG8_STAGE(PG8_SB(0, 1), b2 + hstepB, voffB); PG8_STAGE(PG8_SA(0, 0), a2, voffA);
;             PG8_WAIT_V(8); PG8_WAIT_L(0); PG8_BAR; PG8_MMA(1, 0, At, B0); PG8_MMA(1, 1, At, B1); PG8_BAR; PG8_SCHED;
	v_mfma_f32_16x16x32_bf16 v[126:129], v[146:149], v[186:189], v[126:129]
	v_mfma_f32_16x16x32_bf16 v[122:125], v[162:165], v[186:189], v[122:125]
	v_mfma_f32_16x16x32_bf16 v[110:113], v[146:149], v[194:197], v[110:113]
	v_mfma_f32_16x16x32_bf16 v[106:109], v[162:165], v[194:197], v[106:109]
	v_mfma_f32_16x16x32_bf16 v[94:97], v[146:149], v[202:205], v[94:97]
	v_mfma_f32_16x16x32_bf16 v[90:93], v[162:165], v[202:205], v[90:93]
	v_mfma_f32_16x16x32_bf16 v[78:81], v[146:149], v[210:213], v[78:81]
	v_mfma_f32_16x16x32_bf16 v[74:77], v[162:165], v[210:213], v[74:77]
	v_mfma_f32_16x16x32_bf16 v[126:129], v[158:161], v[190:193], v[126:129]
	v_mfma_f32_16x16x32_bf16 v[122:125], v[166:169], v[190:193], v[122:125]
	v_mfma_f32_16x16x32_bf16 v[110:113], v[158:161], v[198:201], v[110:113]
	v_mfma_f32_16x16x32_bf16 v[106:109], v[166:169], v[198:201], v[106:109]
	v_mfma_f32_16x16x32_bf16 v[94:97], v[158:161], v[206:209], v[94:97]
	v_mfma_f32_16x16x32_bf16 v[90:93], v[166:169], v[206:209], v[90:93]
	v_mfma_f32_16x16x32_bf16 v[78:81], v[158:161], v[214:217], v[78:81]
	v_mfma_f32_16x16x32_bf16 v[74:77], v[166:169], v[214:217], v[74:77]
	v_mfma_f32_16x16x32_bf16 v[118:121], v[170:173], v[186:189], v[118:121]
	v_mfma_f32_16x16x32_bf16 v[114:117], v[178:181], v[186:189], v[114:117]
	v_mfma_f32_16x16x32_bf16 v[102:105], v[170:173], v[194:197], v[102:105]
	v_mfma_f32_16x16x32_bf16 v[98:101], v[178:181], v[194:197], v[98:101]
	v_mfma_f32_16x16x32_bf16 v[86:89], v[170:173], v[202:205], v[86:89]
	v_mfma_f32_16x16x32_bf16 v[82:85], v[178:181], v[202:205], v[82:85]
	v_mfma_f32_16x16x32_bf16 v[70:73], v[170:173], v[210:213], v[70:73]
	v_mfma_f32_16x16x32_bf16 v[66:69], v[178:181], v[210:213], v[66:69]
	v_mfma_f32_16x16x32_bf16 v[118:121], v[174:177], v[190:193], v[118:121]
	v_mfma_f32_16x16x32_bf16 v[114:117], v[182:185], v[190:193], v[114:117]
	v_mfma_f32_16x16x32_bf16 v[102:105], v[174:177], v[198:201], v[102:105]
	v_mfma_f32_16x16x32_bf16 v[98:101], v[182:185], v[198:201], v[98:101]
	v_mfma_f32_16x16x32_bf16 v[86:89], v[174:177], v[206:209], v[86:89]
	v_mfma_f32_16x16x32_bf16 v[82:85], v[182:185], v[206:209], v[82:85]
	v_mfma_f32_16x16x32_bf16 v[70:73], v[174:177], v[214:217], v[70:73]
	v_mfma_f32_16x16x32_bf16 v[66:69], v[182:185], v[214:217], v[66:69]
	s_barrier
	s_add_i32 s62, s57, s30
	v_lshl_add_u64 v[150:151], s[40:41], 0, v[132:133]
	s_mov_b32 m0, s62
	ds_read_b128 v[186:189], v156 offset:16384
	ds_read_b128 v[190:193], v156 offset:17408
	ds_read_b128 v[194:197], v156 offset:18432
	ds_read_b128 v[198:201], v156 offset:19456
	ds_read_b128 v[202:205], v156 offset:20480
	ds_read_b128 v[206:209], v156 offset:21504
	ds_read_b128 v[210:213], v156 offset:22528
	ds_read_b128 v[214:217], v156 offset:23552
	global_load_lds_dwordx4 v132, s[40:41]
	s_add_i32 m0, s62, 0x2000
	s_add_u32 s62, s40, 0x10000
	v_lshl_add_u64 v[218:219], s[40:41], 0, v[136:137]
	s_addc_u32 s63, s41, 0
	s_add_i32 s64, s58, s30
	global_load_lds_dwordx4 v136, s[40:41]
	s_mov_b32 m0, s64
	v_lshl_add_u64 v[222:223], s[42:43], 0, v[134:135]
	global_load_lds_dwordx4 v132, s[62:63]
	s_add_i32 m0, s64, 0x2000
	s_nop 0
	global_load_lds_dwordx4 v136, s[62:63]
	v_lshl_add_u64 v[220:221], s[42:43], 0, v[130:131]
	s_mov_b32 m0, s31
	s_nop 0
	global_load_lds_dwordx4 v130, s[42:43]
	s_mov_b32 m0, s33
	s_nop 0
	global_load_lds_dwordx4 v134, s[42:43]
	s_waitcnt vmcnt(8) lgkmcnt(0)
	s_barrier
	v_mfma_f32_16x16x32_bf16 v[62:65], v[146:149], v[186:189], v[62:65]
	v_mfma_f32_16x16x32_bf16 v[58:61], v[162:165], v[186:189], v[58:61]
	v_mfma_f32_16x16x32_bf16 v[46:49], v[146:149], v[194:197], v[46:49]
	v_mfma_f32_16x16x32_bf16 v[42:45], v[162:165], v[194:197], v[42:45]
	v_mfma_f32_16x16x32_bf16 v[30:33], v[146:149], v[202:205], v[30:33]
	v_mfma_f32_16x16x32_bf16 v[26:29], v[162:165], v[202:205], v[26:29]
	v_mfma_f32_16x16x32_bf16 v[14:17], v[146:149], v[210:213], v[14:17]
	v_mfma_f32_16x16x32_bf16 v[10:13], v[162:165], v[210:213], v[10:13]
	v_mfma_f32_16x16x32_bf16 v[62:65], v[158:161], v[190:193], v[62:65]
	v_mfma_f32_16x16x32_bf16 v[58:61], v[166:169], v[190:193], v[58:61]
	v_mfma_f32_16x16x32_bf16 v[46:49], v[158:161], v[198:201], v[46:49]
	v_mfma_f32_16x16x32_bf16 v[42:45], v[166:169], v[198:201], v[42:45]
	v_mfma_f32_16x16x32_bf16 v[30:33], v[158:161], v[206:209], v[30:33]
	v_mfma_f32_16x16x32_bf16 v[26:29], v[166:169], v[206:209], v[26:29]
	v_mfma_f32_16x16x32_bf16 v[14:17], v[158:161], v[214:217], v[14:17]
	v_mfma_f32_16x16x32_bf16 v[10:13], v[166:169], v[214:217], v[10:13]
	v_mfma_f32_16x16x32_bf16 v[54:57], v[170:173], v[186:189], v[54:57]
	v_mfma_f32_16x16x32_bf16 v[50:53], v[178:181], v[186:189], v[50:53]
	v_mfma_f32_16x16x32_bf16 v[38:41], v[170:173], v[194:197], v[38:41]
	v_mfma_f32_16x16x32_bf16 v[34:37], v[178:181], v[194:197], v[34:37]
	v_mfma_f32_16x16x32_bf16 v[22:25], v[170:173], v[202:205], v[22:25]
	v_mfma_f32_16x16x32_bf16 v[18:21], v[178:181], v[202:205], v[18:21]
	v_mfma_f32_16x16x32_bf16 v[6:9], v[170:173], v[210:213], v[6:9]
	v_mfma_f32_16x16x32_bf16 v[2:5], v[178:181], v[210:213], v[2:5]
	v_mfma_f32_16x16x32_bf16 v[54:57], v[174:177], v[190:193], v[54:57]
	v_mfma_f32_16x16x32_bf16 v[50:53], v[182:185], v[190:193], v[50:53]
	v_mfma_f32_16x16x32_bf16 v[38:41], v[174:177], v[198:201], v[38:41]
	v_mfma_f32_16x16x32_bf16 v[34:37], v[182:185], v[198:201], v[34:37]
	v_mfma_f32_16x16x32_bf16 v[22:25], v[174:177], v[206:209], v[22:25]
	v_mfma_f32_16x16x32_bf16 v[18:21], v[182:185], v[206:209], v[18:21]
	v_mfma_f32_16x16x32_bf16 v[6:9], v[174:177], v[214:217], v[6:9]
	v_mfma_f32_16x16x32_bf16 v[2:5], v[182:185], v[214:217], v[2:5]
	s_barrier
; #define PG8_STAGE(bufoff, gbase, voff) do { _Pragma("unroll") for (int _i = 0; _i < 2; ++_i) \
;         __builtin_amdgcn_global_load_lds((const unsigned*)((const char*)(gbase) + (voff)[_i]), (PG8_LAS unsigned*)(lds + (bufoff) + ldsw + _i * 8192), 16, 0, 0); } while (0)
; #define PG8_LDA(dst, b, h) do { _Pragma("unroll") for (int m = 0; m < 4; ++m) _Pragma("unroll") for (int k = 0; k < 2; ++k) dst[m][k] = *(const PG8_LAS bf16x8*)(lds + PG8_SA(b, h) + aoff + m * 2048 + k * 1024); } while (0)
; #define PG8_LDB(dst, b, h) do { _Pragma("unroll") for (int n = 0; n < 2; ++n) _Pragma("unroll") for (int k = 0; k < 2; ++k) dst[n][k] = *(const PG8_LAS bf16x8*)(lds + PG8_SB(b, h) + boff + n * 2048 + k * 1024); } while (0)
; #define PG8_MMA(ai, bj, At, Bt) do { __builtin_amdgcn_s_setprio(1); _Pragma("unroll") for (int m = 0; m < 4; ++m) _Pragma("unroll") for (int n = 0; n < 2; ++n) _Pragma("unroll") for (int k = 0; k < 2; ++k) \
;         acc[ai][bj][m][n] = __builtin_amdgcn_mfma_f32_16x16x32_bf16(Bt[n][k], At[m][k], acc[ai][bj][m][n], 0, 0, 0); __builtin_amdgcn_s_setprio(0); } while (0)
; #define PG8_WAIT_V(n) asm volatile("s_waitcnt vmcnt(" #n ")" ::: "memory")
; #define PG8_WAIT_L(n) asm volatile("s_waitcnt lgkmcnt(" #n ")" ::: "memory")
; #define PG8_BAR __builtin_amdgcn_s_barrier()
; #define PG8_SCHED __builtin_amdgcn_sched_barrier(0)
; template <class Epi, class Sched, bool ALIGN_EPI = false, bool SP2 = false>
; __device__ __forceinline__ void gemm_phase(PG8_LAS unsigned char* lds, const Gemm g, const Sched& S, const Epi& E) {
;     ...
;             PG8_LDB(B0, 1, 0); PG8_LDB(B1, 1, 1); PG8_SCHED; PG8_LDA(At, 1, 0); PG8_STAGE(PG8_SA(0, 1), a2 + hstep, voffA);
;             PG8_WAIT_V(8); PG8_WAIT_L(0); PG8_BAR; PG8_MMA(0, 0, At, B0); PG8_MMA(0, 1, At, B1); PG8_BAR; PG8_SCHED;
;             PG8_LDA(At, 1, 1); PG8_STAGE(PG8_SB(1, 0), b3, voffB); PG8_STAGE(PG8_SB(1, 1), b3 + hstepB, voffB); PG8_STAGE(PG8_SA(1, 0), a3, voffA);
;             PG8_WAIT_V(8); PG8_WAIT_L(0); PG8_BAR; PG8_MMA(1, 0, At, B0); PG8_MMA(1, 1, At, B1); PG8_BAR; PG8_SCHED;
	s_add_i32 s62, 0, 0x18000
	v_add_u32_e32 v157, s62, v152
	s_add_i32 s63, 0, 0x1c000
	ds_read_b128 v[146:149], v157
	ds_read_b128 v[158:161], v157 offset:1024
	ds_read_b128 v[162:165], v157 offset:2048
	ds_read_b128 v[166:169], v157 offset:3072
	v_add_u32_e32 v157, s63, v152
	ds_read_b128 v[170:173], v157
	ds_read_b128 v[174:177], v157 offset:1024
	ds_read_b128 v[178:181], v157 offset:2048
	ds_read_b128 v[182:185], v157 offset:3072
	s_add_u32 s42, s42, 0x40000
	s_addc_u32 s43, s43, 0
	s_mov_b32 m0, s44
	ds_read_b128 v[186:189], v156 offset:32768
	ds_read_b128 v[190:193], v156 offset:33792
	ds_read_b128 v[194:197], v156 offset:34816
	ds_read_b128 v[198:201], v156 offset:35840
	ds_read_b128 v[202:205], v156 offset:36864
	ds_read_b128 v[206:209], v156 offset:37888
	ds_read_b128 v[210:213], v156 offset:38912
	ds_read_b128 v[214:217], v156 offset:39936
	global_load_lds_dwordx4 v130, s[42:43]
	s_mov_b32 m0, s45
	s_nop 0
	global_load_lds_dwordx4 v134, s[42:43]
	s_waitcnt vmcnt(8) lgkmcnt(0)
	s_barrier
	v_mfma_f32_16x16x32_bf16 v[126:129], v[146:149], v[186:189], v[126:129]
	v_mfma_f32_16x16x32_bf16 v[122:125], v[162:165], v[186:189], v[122:125]
	v_mfma_f32_16x16x32_bf16 v[110:113], v[146:149], v[194:197], v[110:113]
	v_mfma_f32_16x16x32_bf16 v[106:109], v[162:165], v[194:197], v[106:109]
	v_mfma_f32_16x16x32_bf16 v[94:97], v[146:149], v[202:205], v[94:97]
	v_mfma_f32_16x16x32_bf16 v[90:93], v[162:165], v[202:205], v[90:93]
	v_mfma_f32_16x16x32_bf16 v[78:81], v[146:149], v[210:213], v[78:81]
	v_mfma_f32_16x16x32_bf16 v[74:77], v[162:165], v[210:213], v[74:77]
	v_mfma_f32_16x16x32_bf16 v[126:129], v[158:161], v[190:193], v[126:129]
	v_mfma_f32_16x16x32_bf16 v[122:125], v[166:169], v[190:193], v[122:125]
	v_mfma_f32_16x16x32_bf16 v[110:113], v[158:161], v[198:201], v[110:113]
	v_mfma_f32_16x16x32_bf16 v[106:109], v[166:169], v[198:201], v[106:109]
	v_mfma_f32_16x16x32_bf16 v[94:97], v[158:161], v[206:209], v[94:97]
	v_mfma_f32_16x16x32_bf16 v[90:93], v[166:169], v[206:209], v[90:93]
	v_mfma_f32_16x16x32_bf16 v[78:81], v[158:161], v[214:217], v[78:81]
	v_mfma_f32_16x16x32_bf16 v[74:77], v[166:169], v[214:217], v[74:77]
	v_mfma_f32_16x16x32_bf16 v[118:121], v[170:173], v[186:189], v[118:121]
	v_mfma_f32_16x16x32_bf16 v[114:117], v[178:181], v[186:189], v[114:117]
	v_mfma_f32_16x16x32_bf16 v[102:105], v[170:173], v[194:197], v[102:105]
	v_mfma_f32_16x16x32_bf16 v[98:101], v[178:181], v[194:197], v[98:101]
	v_mfma_f32_16x16x32_bf16 v[86:89], v[170:173], v[202:205], v[86:89]
	v_mfma_f32_16x16x32_bf16 v[82:85], v[178:181], v[202:205], v[82:85]
	v_mfma_f32_16x16x32_bf16 v[70:73], v[170:173], v[210:213], v[70:73]
	v_mfma_f32_16x16x32_bf16 v[66:69], v[178:181], v[210:213], v[66:69]
	v_mfma_f32_16x16x32_bf16 v[118:121], v[174:177], v[190:193], v[118:121]
	v_mfma_f32_16x16x32_bf16 v[114:117], v[182:185], v[190:193], v[114:117]
	v_mfma_f32_16x16x32_bf16 v[102:105], v[174:177], v[198:201], v[102:105]
	v_mfma_f32_16x16x32_bf16 v[98:101], v[182:185], v[198:201], v[98:101]
	v_mfma_f32_16x16x32_bf16 v[86:89], v[174:177], v[206:209], v[86:89]
	v_mfma_f32_16x16x32_bf16 v[82:85], v[182:185], v[206:209], v[82:85]
	v_mfma_f32_16x16x32_bf16 v[70:73], v[174:177], v[214:217], v[70:73]
	v_mfma_f32_16x16x32_bf16 v[66:69], v[182:185], v[214:217], v[66:69]
	s_barrier
	s_add_i32 s42, s62, s30
	v_lshl_add_u64 v[150:151], v[150:151], 0, s[10:11]
	s_mov_b32 m0, s42
	ds_read_b128 v[186:189], v156 offset:49152
	ds_read_b128 v[190:193], v156 offset:50176
	ds_read_b128 v[194:197], v156 offset:51200
	ds_read_b128 v[198:201], v156 offset:52224
	ds_read_b128 v[202:205], v156 offset:53248
	ds_read_b128 v[206:209], v156 offset:54272
	ds_read_b128 v[210:213], v156 offset:55296
	ds_read_b128 v[214:217], v156 offset:56320
	global_load_lds_dwordx4 v[150:151], off
	s_add_i32 m0, s42, 0x2000
	s_add_u32 s40, s40, 0x10080
	v_lshl_add_u64 v[150:151], v[218:219], 0, s[10:11]
	s_addc_u32 s41, s41, 0
	s_add_i32 s42, s63, s30
	global_load_lds_dwordx4 v[150:151], off
	s_mov_b32 m0, s42
	s_nop 0
	global_load_lds_dwordx4 v132, s[40:41]
	s_add_i32 m0, s42, 0x2000
	s_nop 0
	global_load_lds_dwordx4 v136, s[40:41]
	v_lshl_add_u64 v[150:151], v[220:221], 0, s[10:11]
	s_mov_b32 m0, s47
	s_nop 0
	global_load_lds_dwordx4 v[150:151], off
	v_lshl_add_u64 v[150:151], v[222:223], 0, s[10:11]
	s_mov_b32 m0, s54
	s_nop 0
	global_load_lds_dwordx4 v[150:151], off
	s_waitcnt vmcnt(8) lgkmcnt(0)
	s_barrier
	v_mfma_f32_16x16x32_bf16 v[62:65], v[146:149], v[186:189], v[62:65]
	v_mfma_f32_16x16x32_bf16 v[58:61], v[162:165], v[186:189], v[58:61]
	v_mfma_f32_16x16x32_bf16 v[46:49], v[146:149], v[194:197], v[46:49]
	v_mfma_f32_16x16x32_bf16 v[42:45], v[162:165], v[194:197], v[42:45]
	v_mfma_f32_16x16x32_bf16 v[30:33], v[146:149], v[202:205], v[30:33]
	v_mfma_f32_16x16x32_bf16 v[26:29], v[162:165], v[202:205], v[26:29]
	v_mfma_f32_16x16x32_bf16 v[14:17], v[146:149], v[210:213], v[14:17]
	v_mfma_f32_16x16x32_bf16 v[10:13], v[162:165], v[210:213], v[10:13]
	v_mfma_f32_16x16x32_bf16 v[62:65], v[158:161], v[190:193], v[62:65]
	v_mfma_f32_16x16x32_bf16 v[58:61], v[166:169], v[190:193], v[58:61]
	v_mfma_f32_16x16x32_bf16 v[46:49], v[158:161], v[198:201], v[46:49]
	v_mfma_f32_16x16x32_bf16 v[42:45], v[166:169], v[198:201], v[42:45]
	v_mfma_f32_16x16x32_bf16 v[30:33], v[158:161], v[206:209], v[30:33]
	v_mfma_f32_16x16x32_bf16 v[26:29], v[166:169], v[206:209], v[26:29]
	v_mfma_f32_16x16x32_bf16 v[14:17], v[158:161], v[214:217], v[14:17]
	v_mfma_f32_16x16x32_bf16 v[10:13], v[166:169], v[214:217], v[10:13]
	v_mfma_f32_16x16x32_bf16 v[54:57], v[170:173], v[186:189], v[54:57]
	v_mfma_f32_16x16x32_bf16 v[50:53], v[178:181], v[186:189], v[50:53]
	v_mfma_f32_16x16x32_bf16 v[38:41], v[170:173], v[194:197], v[38:41]
	v_mfma_f32_16x16x32_bf16 v[34:37], v[178:181], v[194:197], v[34:37]
	v_mfma_f32_16x16x32_bf16 v[22:25], v[170:173], v[202:205], v[22:25]
	v_mfma_f32_16x16x32_bf16 v[18:21], v[178:181], v[202:205], v[18:21]
	v_mfma_f32_16x16x32_bf16 v[6:9], v[170:173], v[210:213], v[6:9]
	v_mfma_f32_16x16x32_bf16 v[2:5], v[178:181], v[210:213], v[2:5]
	v_mfma_f32_16x16x32_bf16 v[54:57], v[174:177], v[190:193], v[54:57]
	v_mfma_f32_16x16x32_bf16 v[50:53], v[182:185], v[190:193], v[50:53]
	v_mfma_f32_16x16x32_bf16 v[38:41], v[174:177], v[198:201], v[38:41]
	v_mfma_f32_16x16x32_bf16 v[34:37], v[182:185], v[198:201], v[34:37]
	v_mfma_f32_16x16x32_bf16 v[22:25], v[174:177], v[206:209], v[22:25]
	v_mfma_f32_16x16x32_bf16 v[18:21], v[182:185], v[206:209], v[18:21]
	v_mfma_f32_16x16x32_bf16 v[6:9], v[174:177], v[214:217], v[6:9]
	v_mfma_f32_16x16x32_bf16 v[2:5], v[182:185], v[214:217], v[2:5]
	s_barrier
	s_add_i32 s61, s61, 2
	s_add_u32 s38, s38, 0x100
	s_addc_u32 s39, s39, 0
	s_add_u32 s59, s59, 0x100
	s_addc_u32 s60, s60, 0
	s_cmp_gt_u32 s61, 13
	s_cbranch_scc0 .LBB0_1313
